# LDS XOR swizzle + XCD-aware tile order + hoisted ks1 fragment reads + skip dead context rows in last layer
# speedup vs baseline: 1.0446x; 1.0446x over previous
; __device__ __forceinline__ void phase_g1(const Params& p, int l, f16* smem) {
;     ...
;   for (int t = blockIdx.x; t < MT * NT; t += gridDim.x) {
;     int m0 = (t / NT) * 128, n0 = (t % NT) * 128;
.LBB0_194:
	s_cmpk_lg_u32 s26, 0x200
	s_cbranch_scc1 .Lxm_orig_g1
	s_cmpk_ge_u32 s20, 0x1800
	s_cbranch_scc1 .Lxm_last_g1
	s_and_b32 s7, s20, 7
	s_mul_i32 s7, s7, 12
	s_lshr_b32 s8, s20, 9
	s_add_i32 s7, s7, s8
	s_lshl_b32 s7, s7, 6
	s_bfe_u32 s8, s20, 0x60003
	s_or_b32 s7, s7, s8
	s_mul_i32 s8, s7, 2731
	s_lshr_b32 s8, s8, 19
	s_mul_i32 s9, s8, 192
	s_sub_i32 s9, s7, s9
	s_lshr_b32 s21, s9, 3
	s_and_b32 s9, s9, 7
	s_lshl_b32 s8, s8, 3
	s_add_i32 s6, s8, s9
	s_branch .Lxm_fin_g1
.Lxm_last_g1:
	s_sub_i32 s9, s20, 0x1800
	s_lshr_b32 s21, s9, 2
	s_and_b32 s9, s9, 3
	s_add_i32 s6, s9, 0x100
.Lxm_fin_g1:
	s_lshl_b32 s14, s6, 7
	s_ashr_i32 s15, s14, 31
	s_branch .Lxm_done_g1

; template <int NJ>
; __device__ __forceinline__ void gemm_tile(const f16* __restrict__ A, int lda, const f16* __restrict__ Bt, int ldb,
;                                           int K, f32x4 (&acc)[4][NJ], f16* sA, f16* sB, const int tid) {
;     ...
;   G_LOAD(ra0, rb0, 0)
;   if (K > 64) G_LOAD(ra1, rb1, 64)
;   __syncthreads();
;   G_STORE(ra0, rb0, 0)
;   if (K > 128) G_LOAD(ra0, rb0, 128)
;   __syncthreads();
; #pragma unroll 1
;   for (int k0 = 0; k0 < K; k0 += 128) {
;     {
;       const int kof = (k0 + 192 < K) ? k0 + 192 : K - 64;
;       G_STEP(0, ra1, rb1, true, true, kof)
.Lxm_done_g1:
	s_lshl_b64 s[6:7], s[14:15], 11
	v_lshl_add_u64 v[156:157], v[154:155], 0, s[6:7]
	v_add_co_u32_e32 v4, vcc, s94, v156
	s_lshl_b32 s16, s21, 7
	s_nop 0
	v_addc_co_u32_e32 v5, vcc, 0, v157, vcc
	v_add_co_u32_e32 v6, vcc, s72, v156
	s_ashr_i32 s17, s16, 31
	s_nop 0
	v_addc_co_u32_e32 v7, vcc, 0, v157, vcc
	s_lshl_b64 s[8:9], s[16:17], 11
	v_add_co_u32_e32 v8, vcc, s73, v156
	v_lshl_add_u64 v[158:159], v[152:153], 0, s[8:9]
	s_nop 0
	v_addc_co_u32_e32 v9, vcc, 0, v157, vcc
	v_add_co_u32_e32 v10, vcc, s94, v158
	global_load_dwordx4 v[18:21], v[156:157], off
	s_nop 0
	v_addc_co_u32_e32 v11, vcc, 0, v159, vcc
	v_add_co_u32_e32 v12, vcc, s72, v158
	global_load_dwordx4 v[22:25], v[4:5], off
	global_load_dwordx4 v[26:29], v[6:7], off
	v_addc_co_u32_e32 v13, vcc, 0, v159, vcc
	v_add_co_u32_e32 v14, vcc, s73, v158
	global_load_dwordx4 v[30:33], v[8:9], off
	global_load_dwordx4 v[38:41], v[10:11], off
	v_addc_co_u32_e32 v15, vcc, 0, v159, vcc
	global_load_dwordx4 v[34:37], v[158:159], off
	global_load_dwordx4 v[42:45], v[12:13], off
	global_load_dwordx4 v[46:49], v[14:15], off
	global_load_dwordx4 v[68:71], v[156:157], off offset:128
	global_load_dwordx4 v[76:79], v[4:5], off offset:128
	global_load_dwordx4 v[80:83], v[6:7], off offset:128
	global_load_dwordx4 v[84:87], v[8:9], off offset:128
	global_load_dwordx4 v[72:75], v[158:159], off offset:128
	global_load_dwordx4 v[88:91], v[10:11], off offset:128
	global_load_dwordx4 v[96:99], v[12:13], off offset:128
	global_load_dwordx4 v[100:103], v[14:15], off offset:128
	s_barrier
	global_load_dwordx4 v[108:111], v[4:5], off offset:256
	global_load_dwordx4 v[112:115], v[6:7], off offset:256
	global_load_dwordx4 v[92:95], v[156:157], off offset:256
	global_load_dwordx4 v[104:107], v[158:159], off offset:256
	global_load_dwordx4 v[116:119], v[8:9], off offset:256
	global_load_dwordx4 v[120:123], v[10:11], off offset:256
	global_load_dwordx4 v[124:127], v[12:13], off offset:256
	global_load_dwordx4 v[128:131], v[14:15], off offset:256
	v_mov_b32_e32 v4, 0
	s_mov_b32 s6, 0
	v_mov_b32_e32 v5, v4
	v_mov_b32_e32 v6, v4
	v_mov_b32_e32 v7, v4
	v_mov_b32_e32 v8, v4
	v_mov_b32_e32 v9, v4
	v_mov_b32_e32 v10, v4
	v_mov_b32_e32 v11, v4
	v_mov_b32_e32 v12, v4
	v_mov_b32_e32 v13, v4
	v_mov_b32_e32 v14, v4
	v_mov_b32_e32 v15, v4
	v_mov_b32_e32 v16, v4
	v_mov_b32_e32 v17, v4
	v_mov_b32_e32 v50, v4
	v_mov_b32_e32 v51, v4
	v_mov_b32_e32 v52, v4
	v_mov_b32_e32 v53, v4
	v_mov_b32_e32 v54, v4
	v_mov_b32_e32 v55, v4
	v_mov_b32_e32 v56, v4
	v_mov_b32_e32 v57, v4
	v_mov_b32_e32 v58, v4
	v_mov_b32_e32 v59, v4
	v_mov_b32_e32 v60, v4
	v_mov_b32_e32 v61, v4
	v_mov_b32_e32 v62, v4
	v_mov_b32_e32 v63, v4
	v_mov_b32_e32 v64, v4
	v_mov_b32_e32 v65, v4
	v_mov_b32_e32 v66, v4
	v_mov_b32_e32 v67, v4
	s_waitcnt vmcnt(23)
	ds_write_b128 v167, v[18:21]
	s_waitcnt vmcnt(22)
	ds_write_b128 v167, v[22:25] offset:4096
	s_waitcnt vmcnt(21)
	ds_write_b128 v167, v[26:29] offset:8192
	s_waitcnt vmcnt(20)
	ds_write_b128 v167, v[30:33] offset:12288
	s_waitcnt vmcnt(18)
	ds_write_b128 v167, v[34:37] offset:16384
	ds_write_b128 v167, v[38:41] offset:20480
	s_waitcnt vmcnt(17)
	ds_write_b128 v167, v[42:45] offset:24576
	s_waitcnt vmcnt(16)
	ds_write_b128 v167, v[46:49] offset:28672
	v_mov_b32_e32 v18, v4
	v_mov_b32_e32 v19, v4
	v_mov_b32_e32 v20, v4
	v_mov_b32_e32 v21, v4
	v_mov_b32_e32 v22, v4
	v_mov_b32_e32 v23, v4
	v_mov_b32_e32 v24, v4
	v_mov_b32_e32 v25, v4
	v_mov_b32_e32 v26, v4
	v_mov_b32_e32 v27, v4
	v_mov_b32_e32 v28, v4
	v_mov_b32_e32 v29, v4
	v_mov_b32_e32 v30, v4
	v_mov_b32_e32 v31, v4
	v_mov_b32_e32 v32, v4
	v_mov_b32_e32 v33, v4
	v_mov_b32_e32 v34, v4
	v_mov_b32_e32 v35, v4
	v_mov_b32_e32 v36, v4
	v_mov_b32_e32 v37, v4
	v_mov_b32_e32 v38, v4
	v_mov_b32_e32 v39, v4
	v_mov_b32_e32 v40, v4
	v_mov_b32_e32 v41, v4
	v_mov_b32_e32 v42, v4
	v_mov_b32_e32 v43, v4
	v_mov_b32_e32 v44, v4
	v_mov_b32_e32 v45, v4
	v_mov_b32_e32 v46, v4
	v_mov_b32_e32 v47, v4
	v_mov_b32_e32 v48, v4
	v_mov_b32_e32 v49, v4
	s_waitcnt lgkmcnt(0)
	s_barrier
.LBB0_195:
	ds_read_b128 v[204:207], v168 offset:16384
	ds_read_b128 v[208:211], v168 offset:18432
	ds_read_b128 v[212:215], v168 offset:20480
	ds_read_b128 v[216:219], v168 offset:22528
	s_add_i32 s7, s6, 0xc0
	ds_read_b128 v[192:195], v170
	ds_read_b128 v[196:199], v170 offset:2048
	s_cmpk_lt_u32 s6, 0x340
	s_cselect_b32 s42, s7, 0x3c0
	ds_read_b128 v[200:203], v170 offset:4096
	s_lshl_b64 s[8:9], s[42:43], 1
	v_lshl_add_u64 v[162:163], v[156:157], 0, s[8:9]
	ds_read_b128 v[132:135], v170 offset:6144
	ds_read_b128 v[244:247], v243 offset:16384
	ds_read_b128 v[248:251], v243 offset:18432
	ds_read_b128 v[252:255], v243 offset:20480
	s_waitcnt lgkmcnt(6)
	v_mfma_f32_16x16x32_f16 v[64:67], v[204:207], v[192:195], v[64:67]
	v_lshl_add_u64 v[160:161], v[158:159], 0, s[8:9]
	s_add_i32 s7, s6, 0x100
	s_cmpk_lt_u32 s6, 0x300
	v_mfma_f32_16x16x32_f16 v[60:63], v[208:211], v[192:195], v[60:63]
	s_cselect_b32 s42, s7, 0x3c0
	s_lshl_b64 s[8:9], s[42:43], 1
	s_add_i32 s7, s6, 0x80
	v_mfma_f32_16x16x32_f16 v[56:59], v[212:215], v[192:195], v[56:59]
	s_cmpk_lt_u32 s6, 0x380
	s_mov_b32 s6, s7
	v_mfma_f32_16x16x32_f16 v[52:55], v[216:219], v[192:195], v[52:55]
	ds_read_b128 v[192:195], v243 offset:22528
	s_waitcnt vmcnt(15)
	ds_write_b128 v167, v[68:71] offset:32768
	global_load_dwordx4 v[68:71], v[162:163], off
	s_waitcnt lgkmcnt(7)
	v_mfma_f32_16x16x32_f16 v[48:51], v[204:207], v[196:199], v[48:51]
	v_mfma_f32_16x16x32_f16 v[44:47], v[208:211], v[196:199], v[44:47]
	v_mfma_f32_16x16x32_f16 v[40:43], v[212:215], v[196:199], v[40:43]
	v_mfma_f32_16x16x32_f16 v[36:39], v[216:219], v[196:199], v[36:39]
	ds_read_b128 v[196:199], v242
	s_waitcnt vmcnt(15)
	ds_write_b128 v167, v[76:79] offset:36864
	v_add_co_u32_e32 v76, vcc, s94, v162
	s_nop 1
	v_addc_co_u32_e32 v77, vcc, 0, v163, vcc
	global_load_dwordx4 v[76:79], v[76:77], off
	s_waitcnt lgkmcnt(8)
	v_mfma_f32_16x16x32_f16 v[32:35], v[204:207], v[200:203], v[32:35]
	v_mfma_f32_16x16x32_f16 v[28:31], v[208:211], v[200:203], v[28:31]
	v_mfma_f32_16x16x32_f16 v[24:27], v[212:215], v[200:203], v[24:27]
	v_mfma_f32_16x16x32_f16 v[20:23], v[216:219], v[200:203], v[20:23]
	ds_read_b128 v[200:203], v242 offset:2048
	s_waitcnt vmcnt(15)
	ds_write_b128 v167, v[80:83] offset:40960
	v_add_co_u32_e32 v80, vcc, s72, v162
	s_nop 1
	v_addc_co_u32_e32 v81, vcc, 0, v163, vcc
	global_load_dwordx4 v[80:83], v[80:81], off
	s_waitcnt lgkmcnt(9)
	v_mfma_f32_16x16x32_f16 v[16:19], v[204:207], v[132:135], v[16:19]
	v_mfma_f32_16x16x32_f16 v[12:15], v[208:211], v[132:135], v[12:15]
	v_mfma_f32_16x16x32_f16 v[8:11], v[212:215], v[132:135], v[8:11]
	v_mfma_f32_16x16x32_f16 v[4:7], v[216:219], v[132:135], v[4:7]
	ds_read_b128 v[132:135], v242 offset:4096
	ds_read_b128 v[204:207], v242 offset:6144
	s_waitcnt vmcnt(15)
	ds_write_b128 v167, v[84:87] offset:45056
	v_add_co_u32_e32 v84, vcc, s73, v162
	s_nop 1
	v_addc_co_u32_e32 v85, vcc, 0, v163, vcc
	global_load_dwordx4 v[84:87], v[84:85], off
	s_waitcnt lgkmcnt(6)
	v_mfma_f32_16x16x32_f16 v[64:67], v[244:247], v[196:199], v[64:67]
	v_mfma_f32_16x16x32_f16 v[60:63], v[248:251], v[196:199], v[60:63]
	v_mfma_f32_16x16x32_f16 v[56:59], v[252:255], v[196:199], v[56:59]
	v_mfma_f32_16x16x32_f16 v[52:55], v[192:195], v[196:199], v[52:55]
	s_waitcnt vmcnt(15)
	ds_write_b128 v167, v[72:75] offset:49152
	global_load_dwordx4 v[72:75], v[160:161], off
	v_lshl_add_u64 v[218:219], v[156:157], 0, s[8:9]
	s_waitcnt lgkmcnt(5)
	v_mfma_f32_16x16x32_f16 v[48:51], v[244:247], v[200:203], v[48:51]
	v_lshl_add_u64 v[216:217], v[158:159], 0, s[8:9]
	v_mfma_f32_16x16x32_f16 v[44:47], v[248:251], v[200:203], v[44:47]
	v_mfma_f32_16x16x32_f16 v[40:43], v[252:255], v[200:203], v[40:43]
	v_mfma_f32_16x16x32_f16 v[36:39], v[192:195], v[200:203], v[36:39]
	s_waitcnt vmcnt(15)
	ds_write_b128 v167, v[88:91] offset:53248
	v_add_co_u32_e32 v88, vcc, s94, v160
	s_nop 1
	v_addc_co_u32_e32 v89, vcc, 0, v161, vcc
	global_load_dwordx4 v[88:91], v[88:89], off
	s_waitcnt lgkmcnt(4)
	v_mfma_f32_16x16x32_f16 v[32:35], v[244:247], v[132:135], v[32:35]
	v_mfma_f32_16x16x32_f16 v[28:31], v[248:251], v[132:135], v[28:31]
	v_mfma_f32_16x16x32_f16 v[24:27], v[252:255], v[132:135], v[24:27]
	v_mfma_f32_16x16x32_f16 v[20:23], v[192:195], v[132:135], v[20:23]
	s_waitcnt vmcnt(15)
	ds_write_b128 v167, v[96:99] offset:57344
	v_add_co_u32_e32 v96, vcc, s72, v160
	s_nop 1
	v_addc_co_u32_e32 v97, vcc, 0, v161, vcc
	global_load_dwordx4 v[96:99], v[96:97], off
	s_waitcnt lgkmcnt(4)
	v_mfma_f32_16x16x32_f16 v[16:19], v[244:247], v[204:207], v[16:19]
	v_mfma_f32_16x16x32_f16 v[12:15], v[248:251], v[204:207], v[12:15]
	v_mfma_f32_16x16x32_f16 v[8:11], v[252:255], v[204:207], v[8:11]
	v_mfma_f32_16x16x32_f16 v[4:7], v[192:195], v[204:207], v[4:7]
	s_waitcnt vmcnt(15)
	ds_write_b128 v167, v[100:103] offset:61440
	v_add_co_u32_e32 v100, vcc, s73, v160
	s_nop 1
	v_addc_co_u32_e32 v101, vcc, 0, v161, vcc
	global_load_dwordx4 v[100:103], v[100:101], off
	s_waitcnt lgkmcnt(0)
	s_barrier
; template <int NJ>
; __device__ __forceinline__ void gemm_tile(const f16* __restrict__ A, int lda, const f16* __restrict__ Bt, int ldb,
;                                           int K, f32x4 (&acc)[4][NJ], f16* sA, f16* sB, const int tid) {
;     ...
;   for (int k0 = 0; k0 < K; k0 += 128) {
;     {
;       const int kof = (k0 + 192 < K) ? k0 + 192 : K - 64;
;       G_STEP(0, ra1, rb1, true, true, kof)
;     }
;     __syncthreads();
;     if (k0 + 64 >= K) break;
;     {
;       const int kof = (k0 + 256 < K) ? k0 + 256 : K - 64;
;       G_STEP(1, ra0, rb0, true, true, kof)
;     }
;     __syncthreads();
;   }
; __device__ __forceinline__ void phase_g1(const Params& p, int l, f16* smem) {
;     ...
;     } else {
; #pragma unroll
;       for (int i = 0; i < 4; ++i) {
;         int m = m0 + wm * 64 + i * 16 + (lane & 15);
; #pragma unroll
;         for (int j = 0; j < 4; ++j) {
;           int n = n0 + wn * 64 + j * 16 + 4 * (lane >> 4);
;           if (n < N1) {
;             f16x4 o;
;             o[0] = (f16)acc[i][j][0];
;             o[1] = (f16)acc[i][j][1];
;             o[2] = (f16)acc[i][j][2];
;             o[3] = (f16)acc[i][j][3];
;             *(f16x4*)(proj + (size_t)m * PJ + (n - 384)) = o;
	ds_read_b128 v[200:203], v168 offset:49152
	ds_read_b128 v[204:207], v168 offset:51200
	ds_read_b128 v[208:211], v168 offset:53248
	ds_read_b128 v[212:215], v168 offset:55296
	ds_read_b128 v[132:135], v170 offset:32768
	ds_read_b128 v[160:163], v170 offset:34816
	ds_read_b128 v[192:195], v170 offset:36864
	ds_read_b128 v[196:199], v170 offset:38912
	ds_read_b128 v[244:247], v243 offset:49152
	ds_read_b128 v[248:251], v243 offset:51200
	ds_read_b128 v[252:255], v243 offset:53248
	s_waitcnt lgkmcnt(6)
	v_mfma_f32_16x16x32_f16 v[64:67], v[200:203], v[132:135], v[64:67]
	v_mfma_f32_16x16x32_f16 v[60:63], v[204:207], v[132:135], v[60:63]
	v_mfma_f32_16x16x32_f16 v[56:59], v[208:211], v[132:135], v[56:59]
	v_mfma_f32_16x16x32_f16 v[52:55], v[212:215], v[132:135], v[52:55]
	ds_read_b128 v[132:135], v243 offset:55296
	s_waitcnt vmcnt(13)
	ds_write_b128 v167, v[92:95]
	global_load_dwordx4 v[92:95], v[218:219], off
	s_waitcnt lgkmcnt(7)
	v_mfma_f32_16x16x32_f16 v[48:51], v[200:203], v[160:163], v[48:51]
	v_mfma_f32_16x16x32_f16 v[44:47], v[204:207], v[160:163], v[44:47]
	v_mfma_f32_16x16x32_f16 v[40:43], v[208:211], v[160:163], v[40:43]
	v_mfma_f32_16x16x32_f16 v[36:39], v[212:215], v[160:163], v[36:39]
	ds_read_b128 v[160:163], v242 offset:32768
	ds_write_b128 v167, v[108:111] offset:4096
	v_add_co_u32_e32 v108, vcc, s94, v218
	s_nop 1
	v_addc_co_u32_e32 v109, vcc, 0, v219, vcc
	global_load_dwordx4 v[108:111], v[108:109], off
	s_waitcnt lgkmcnt(8)
	v_mfma_f32_16x16x32_f16 v[32:35], v[200:203], v[192:195], v[32:35]
	v_mfma_f32_16x16x32_f16 v[28:31], v[204:207], v[192:195], v[28:31]
	v_mfma_f32_16x16x32_f16 v[24:27], v[208:211], v[192:195], v[24:27]
	v_mfma_f32_16x16x32_f16 v[20:23], v[212:215], v[192:195], v[20:23]
	ds_read_b128 v[192:195], v242 offset:34816
	ds_write_b128 v167, v[112:115] offset:8192
	v_add_co_u32_e32 v112, vcc, s72, v218
	s_nop 1
	v_addc_co_u32_e32 v113, vcc, 0, v219, vcc
	global_load_dwordx4 v[112:115], v[112:113], off
	s_waitcnt lgkmcnt(9)
	v_mfma_f32_16x16x32_f16 v[16:19], v[200:203], v[196:199], v[16:19]
	v_mfma_f32_16x16x32_f16 v[12:15], v[204:207], v[196:199], v[12:15]
	v_mfma_f32_16x16x32_f16 v[8:11], v[208:211], v[196:199], v[8:11]
	v_mfma_f32_16x16x32_f16 v[4:7], v[212:215], v[196:199], v[4:7]
	ds_read_b128 v[196:199], v242 offset:36864
	ds_read_b128 v[200:203], v242 offset:38912
	s_waitcnt vmcnt(14)
	ds_write_b128 v167, v[116:119] offset:12288
	v_add_co_u32_e32 v116, vcc, s73, v218
	s_nop 1
	v_addc_co_u32_e32 v117, vcc, 0, v219, vcc
	global_load_dwordx4 v[116:119], v[116:117], off
	s_waitcnt lgkmcnt(6)
	v_mfma_f32_16x16x32_f16 v[64:67], v[244:247], v[160:163], v[64:67]
	v_mfma_f32_16x16x32_f16 v[60:63], v[248:251], v[160:163], v[60:63]
	v_mfma_f32_16x16x32_f16 v[56:59], v[252:255], v[160:163], v[56:59]
	v_mfma_f32_16x16x32_f16 v[52:55], v[132:135], v[160:163], v[52:55]
	ds_write_b128 v167, v[104:107] offset:16384
	global_load_dwordx4 v[104:107], v[216:217], off
	s_waitcnt lgkmcnt(5)
	v_mfma_f32_16x16x32_f16 v[48:51], v[244:247], v[192:195], v[48:51]
	v_mfma_f32_16x16x32_f16 v[44:47], v[248:251], v[192:195], v[44:47]
	v_mfma_f32_16x16x32_f16 v[40:43], v[252:255], v[192:195], v[40:43]
	v_mfma_f32_16x16x32_f16 v[36:39], v[132:135], v[192:195], v[36:39]
	s_waitcnt vmcnt(15)
	ds_write_b128 v167, v[120:123] offset:20480
	v_add_co_u32_e32 v120, vcc, s94, v216
	s_nop 1
	v_addc_co_u32_e32 v121, vcc, 0, v217, vcc
	global_load_dwordx4 v[120:123], v[120:121], off
	s_waitcnt lgkmcnt(4)
	v_mfma_f32_16x16x32_f16 v[32:35], v[244:247], v[196:199], v[32:35]
	v_mfma_f32_16x16x32_f16 v[28:31], v[248:251], v[196:199], v[28:31]
	v_mfma_f32_16x16x32_f16 v[24:27], v[252:255], v[196:199], v[24:27]
	v_mfma_f32_16x16x32_f16 v[20:23], v[132:135], v[196:199], v[20:23]
	s_waitcnt vmcnt(15)
	ds_write_b128 v167, v[124:127] offset:24576
	v_add_co_u32_e32 v124, vcc, s72, v216
	s_nop 1
	v_addc_co_u32_e32 v125, vcc, 0, v217, vcc
	global_load_dwordx4 v[124:127], v[124:125], off
	s_waitcnt lgkmcnt(4)
	v_mfma_f32_16x16x32_f16 v[16:19], v[244:247], v[200:203], v[16:19]
	v_mfma_f32_16x16x32_f16 v[12:15], v[248:251], v[200:203], v[12:15]
	v_mfma_f32_16x16x32_f16 v[8:11], v[252:255], v[200:203], v[8:11]
	v_mfma_f32_16x16x32_f16 v[4:7], v[132:135], v[200:203], v[4:7]
	s_waitcnt vmcnt(15)
	ds_write_b128 v167, v[128:131] offset:28672
	v_add_co_u32_e32 v128, vcc, s73, v216
	s_nop 1
	v_addc_co_u32_e32 v129, vcc, 0, v217, vcc
	global_load_dwordx4 v[128:131], v[128:129], off
	s_waitcnt lgkmcnt(0)
	s_barrier
	s_cbranch_scc1 .LBB0_195
	s_cmp_gt_i32 s21, 5
	s_mov_b64 s[6:7], -1
	s_cbranch_scc0 .LBB0_210
	s_cmp_lt_u32 s21, 9
	s_cbranch_scc1 .LBB0_232
	s_waitcnt vmcnt(15)
	v_add_u32_e32 v70, s14, v143
	v_or_b32_e32 v164, s16, v166
	v_mad_i64_i32 v[68:69], s[6:7], v70, s22, v[144:145]
	v_cmp_gt_i32_e32 vcc, s62, v164
	s_and_saveexec_b64 s[6:7], vcc
	s_cbranch_execz .LBB0_200
	s_waitcnt vmcnt(11)
	v_cvt_pk_f16_f32 v73, v66, v67
	v_cvt_pk_f16_f32 v72, v64, v65
	v_lshl_add_u64 v[74:75], v[164:165], 1, v[68:69]
	global_store_dwordx2 v[74:75], v[72:73], off offset:-768

; __device__ __forceinline__ void phase_g2(const Params& p, int l, f16* smem) {
;     ...
;   for (int t = blockIdx.x; t < MT * NT; t += gridDim.x) {
;     int m0 = (t / NT) * 128, n0 = (t % NT) * 128;
;     f16x4 am[4][4];
; #pragma unroll
;     for (int i = 0; i < 4; ++i)
; #pragma unroll
;       for (int j = 0; j < 4; ++j)
; #pragma unroll
;         for (int r = 0; r < 4; ++r) am[i][j][r] = (f16)0.f;
;     ...
; #pragma unroll
;     for (int i = 0; i < 4; ++i) {
;       int m = m0 + wm * 64 + i * 16 + (lane & 15);
; #pragma unroll
;       for (int j = 0; j < 4; ++j) {
;         int n = n0 + wn * 64 + j * 16 + 4 * (lane >> 4);
;         *(f16x4*)(mrg + (size_t)m * DM + n) = am[i][j];
;       }
;     }
.LBB0_1112:
	v_add_u32_e32 v0, s6, v159
	v_or_b32_e32 v2, s8, v160
	v_ashrrev_i32_e32 v1, 31, v0
	v_lshlrev_b64 v[4:5], 11, v[0:1]
	v_ashrrev_i32_e32 v3, 31, v2
	v_lshl_add_u64 v[4:5], v[66:67], 0, v[4:5]
	v_lshlrev_b64 v[2:3], 1, v[2:3]
	v_lshl_add_u64 v[4:5], v[4:5], 0, v[2:3]
	global_store_dwordx2 v[4:5], v[112:113], off
	global_store_dwordx2 v[4:5], v[108:109], off offset:32
	global_store_dwordx2 v[4:5], v[106:107], off offset:64
	global_store_dwordx2 v[4:5], v[104:105], off offset:96
	v_or_b32_e32 v4, 16, v0
	v_ashrrev_i32_e32 v5, 31, v4
	v_lshlrev_b64 v[4:5], 11, v[4:5]
	v_lshl_add_u64 v[4:5], v[66:67], 0, v[4:5]
	v_lshl_add_u64 v[4:5], v[4:5], 0, v[2:3]
	global_store_dwordx2 v[4:5], v[102:103], off
	global_store_dwordx2 v[4:5], v[100:101], off offset:32
	global_store_dwordx2 v[4:5], v[98:99], off offset:64
	global_store_dwordx2 v[4:5], v[96:97], off offset:96
	v_or_b32_e32 v4, 32, v0
	v_or_b32_e32 v0, 48, v0
	v_ashrrev_i32_e32 v5, 31, v4
	v_ashrrev_i32_e32 v1, 31, v0
	v_lshlrev_b64 v[4:5], 11, v[4:5]
	v_lshlrev_b64 v[0:1], 11, v[0:1]
	v_lshl_add_u64 v[4:5], v[66:67], 0, v[4:5]
	v_lshl_add_u64 v[0:1], v[66:67], 0, v[0:1]
	s_add_i32 s5, s5, s26
	v_lshl_add_u64 v[4:5], v[4:5], 0, v[2:3]
	v_lshl_add_u64 v[0:1], v[0:1], 0, v[2:3]
	s_movk_i32 s10, 0x81f
	s_cmp_eq_u32 s4, 3
	s_cselect_b32 s10, 0x7ff, s10
	s_cmp_gt_i32 s5, s10
	global_store_dwordx2 v[4:5], v[94:95], off
	global_store_dwordx2 v[4:5], v[92:93], off offset:32
	global_store_dwordx2 v[4:5], v[90:91], off offset:64
	global_store_dwordx2 v[4:5], v[88:89], off offset:96
	global_store_dwordx2 v[0:1], v[86:87], off
	global_store_dwordx2 v[0:1], v[84:85], off offset:32
	global_store_dwordx2 v[0:1], v[82:83], off offset:64
	global_store_dwordx2 v[0:1], v[80:81], off offset:96
	s_cbranch_scc1 .LBB0_1127
.LBB0_1113:
	s_mov_b32 s8, s5
	s_cmpk_lg_u32 s26, 0x200
	s_cbranch_scc1 .Lxm_g2
	s_cmpk_ge_u32 s5, 0x800
	s_cbranch_scc1 .Lxm_g2
	s_and_b32 s8, s5, 7
	s_lshl_b32 s8, s8, 2
	s_lshr_b32 s9, s5, 9
	s_add_i32 s8, s8, s9
	s_lshl_b32 s8, s8, 6
	s_bfe_u32 s9, s5, 0x60003
	s_or_b32 s8, s8, s9
.Lxm_g2:
	s_ashr_i32 s6, s8, 31
	s_lshr_b32 s6, s6, 29
	s_add_i32 s6, s8, s6
	s_and_b32 s7, s6, 0x1fffff8
	s_lshl_b32 s6, s6, 4
	s_sub_i32 s7, s8, s7
	s_and_b32 s6, s6, 0xffffff80
	s_lshl_b32 s8, s7, 7
	s_ashr_i32 s7, s6, 31
	s_lshl_b64 s[10:11], s[6:7], 11
	s_ashr_i32 s9, s8, 31
	v_lshl_add_u64 v[110:111], v[70:71], 0, s[10:11]
	v_lshl_add_u64 v[114:115], v[74:75], 0, s[10:11]
	v_lshl_add_u64 v[116:117], v[64:65], 0, s[10:11]
	s_lshl_b64 s[10:11], s[8:9], 1
	s_or_b32 s7, s8, 32
	s_or_b32 s12, s10, 64
	s_mov_b32 s13, s11
	s_mov_b32 s9, 0
	v_mov_b32_e32 v168, 0
	s_mov_b32 s14, s8
	v_mov_b32_e32 v80, 0
	v_mov_b32_e32 v81, 0
	v_mov_b32_e32 v82, 0
	v_mov_b32_e32 v83, 0
	v_mov_b32_e32 v84, 0
	v_mov_b32_e32 v85, 0
	v_mov_b32_e32 v86, 0
	v_mov_b32_e32 v87, 0
	v_mov_b32_e32 v88, 0
	v_mov_b32_e32 v89, 0
	v_mov_b32_e32 v90, 0
	v_mov_b32_e32 v91, 0
	v_mov_b32_e32 v92, 0
	v_mov_b32_e32 v93, 0
	v_mov_b32_e32 v94, 0
	v_mov_b32_e32 v95, 0
	v_mov_b32_e32 v96, 0
	v_mov_b32_e32 v97, 0
	v_mov_b32_e32 v98, 0
	v_mov_b32_e32 v99, 0
	v_mov_b32_e32 v100, 0
	v_mov_b32_e32 v101, 0
	v_mov_b32_e32 v102, 0
	v_mov_b32_e32 v103, 0
	v_mov_b32_e32 v104, 0
	v_mov_b32_e32 v105, 0
	v_mov_b32_e32 v106, 0
	v_mov_b32_e32 v107, 0
	v_mov_b32_e32 v108, 0
	v_mov_b32_e32 v109, 0
	v_mov_b32_e32 v112, 0
	v_mov_b32_e32 v113, 0
	s_branch .LBB0_1115

; template <int NJ>
; __device__ __forceinline__ void gemm_tile(const f16* __restrict__ A, int lda, const f16* __restrict__ Bt, int ldb,
;                                           int K, f32x4 (&acc)[4][NJ], f16* sA, f16* sB, const int tid) {
;     ...
;   G_LOAD(ra0, rb0, 0)
;   if (K > 64) G_LOAD(ra1, rb1, 64)
;   __syncthreads();
;   G_STORE(ra0, rb0, 0)
;   if (K > 128) G_LOAD(ra0, rb0, 128)
;   __syncthreads();
; __device__ __forceinline__ void phase_gres(const Params& p, int l, const f16* A, int lda, const f16* W, int K, int gate_idx,
;                            bool first_in, f16* smem) {
;     ...
;   const int full = (MT * NT / (int)gridDim.x) * (int)gridDim.x;
;   for (int t = blockIdx.x; t < full; t += gridDim.x)
;     gres_tile<4>(p, A, lda, W, K, mod, first_in, sA, sB, (t / NT) * 128, (t % NT) * 128);
.LBB0_1185:
	s_mov_b32 s12, s5
	s_cmpk_lg_u32 s26, 0x200
	s_cbranch_scc1 .Lxm_g3
	s_cmpk_ge_u32 s5, 0x800
	s_cbranch_scc1 .Lxm_g3
	s_and_b32 s12, s5, 7
	s_lshl_b32 s12, s12, 2
	s_lshr_b32 s13, s5, 9
	s_add_i32 s12, s12, s13
	s_lshl_b32 s12, s12, 6
	s_bfe_u32 s13, s5, 0x60003
	s_or_b32 s12, s12, s13
.Lxm_g3:
	s_ashr_i32 s8, s12, 31
	s_lshr_b32 s8, s8, 29
	s_add_i32 s9, s12, s8
	s_lshl_b32 s8, s9, 4
	s_and_b32 s9, s9, 0x1fffff8
	s_and_b32 s8, s8, 0xffffff80
	s_sub_i32 s9, s12, s9
	s_lshl_b32 s12, s9, 7
	s_ashr_i32 s9, s8, 31
	s_lshl_b64 s[10:11], s[8:9], 11
	v_lshl_add_u64 v[154:155], v[148:149], 0, s[10:11]
	v_add_co_u32_e32 v2, vcc, s94, v154
	s_ashr_i32 s13, s12, 31
	s_nop 0
	v_addc_co_u32_e32 v3, vcc, 0, v155, vcc
	v_add_co_u32_e32 v4, vcc, s72, v154
	s_lshl_b64 s[14:15], s[12:13], 11
	s_nop 0
	v_addc_co_u32_e32 v5, vcc, 0, v155, vcc
	v_add_co_u32_e32 v6, vcc, s73, v154
	v_lshl_add_u64 v[156:157], v[150:151], 0, s[14:15]
	s_nop 0
	v_addc_co_u32_e32 v7, vcc, 0, v155, vcc
	v_add_co_u32_e32 v8, vcc, s94, v156
	global_load_dwordx4 v[16:19], v[154:155], off
	s_nop 0
	v_addc_co_u32_e32 v9, vcc, 0, v157, vcc
	v_add_co_u32_e32 v10, vcc, s72, v156
	global_load_dwordx4 v[20:23], v[2:3], off
	s_nop 0
	v_addc_co_u32_e32 v11, vcc, 0, v157, vcc
	v_add_co_u32_e32 v12, vcc, s73, v156
	global_load_dwordx4 v[24:27], v[4:5], off
	s_nop 0
	v_addc_co_u32_e32 v13, vcc, 0, v157, vcc
	global_load_dwordx4 v[28:31], v[6:7], off
	global_load_dwordx4 v[98:101], v[156:157], off
	global_load_dwordx4 v[102:105], v[8:9], off
	global_load_dwordx4 v[106:109], v[10:11], off
	global_load_dwordx4 v[110:113], v[12:13], off
	global_load_dwordx4 v[34:37], v[154:155], off offset:128
	global_load_dwordx4 v[42:45], v[2:3], off offset:128
	global_load_dwordx4 v[46:49], v[4:5], off offset:128
	global_load_dwordx4 v[50:53], v[6:7], off offset:128
	global_load_dwordx4 v[38:41], v[156:157], off offset:128
	global_load_dwordx4 v[54:57], v[8:9], off offset:128
	global_load_dwordx4 v[62:65], v[10:11], off offset:128
	global_load_dwordx4 v[66:69], v[12:13], off offset:128
	s_barrier
	global_load_dwordx4 v[74:77], v[2:3], off offset:256
	global_load_dwordx4 v[78:81], v[4:5], off offset:256
	global_load_dwordx4 v[58:61], v[154:155], off offset:256
	global_load_dwordx4 v[70:73], v[156:157], off offset:256
	global_load_dwordx4 v[82:85], v[6:7], off offset:256
	global_load_dwordx4 v[86:89], v[8:9], off offset:256
	global_load_dwordx4 v[90:93], v[10:11], off offset:256
	global_load_dwordx4 v[94:97], v[12:13], off offset:256
	v_mov_b32_e32 v2, 0
	s_mov_b32 s9, 0
	v_mov_b32_e32 v3, v2
	v_mov_b32_e32 v4, v2
	v_mov_b32_e32 v5, v2
	v_mov_b32_e32 v6, v2
	v_mov_b32_e32 v7, v2
	v_mov_b32_e32 v8, v2
	v_mov_b32_e32 v9, v2
	v_mov_b32_e32 v10, v2
	v_mov_b32_e32 v11, v2
	v_mov_b32_e32 v12, v2
	v_mov_b32_e32 v13, v2
	v_mov_b32_e32 v14, v2
	v_mov_b32_e32 v15, v2
	v_mov_b32_e32 v32, v2
	v_mov_b32_e32 v33, v2
	v_mov_b32_e32 v114, v2
	v_mov_b32_e32 v115, v2
	v_mov_b32_e32 v116, v2
	v_mov_b32_e32 v117, v2
	v_mov_b32_e32 v118, v2
	v_mov_b32_e32 v119, v2
	v_mov_b32_e32 v120, v2
	v_mov_b32_e32 v121, v2
	v_mov_b32_e32 v122, v2
	v_mov_b32_e32 v123, v2
	v_mov_b32_e32 v124, v2
	v_mov_b32_e32 v125, v2
	v_mov_b32_e32 v126, v2
	v_mov_b32_e32 v127, v2
	v_mov_b32_e32 v128, v2
	v_mov_b32_e32 v129, v2
	s_waitcnt vmcnt(23)
	ds_write_b128 v169, v[16:19]
	s_waitcnt vmcnt(22)
	ds_write_b128 v169, v[20:23] offset:4096
	s_waitcnt vmcnt(21)
	ds_write_b128 v169, v[24:27] offset:8192
	s_waitcnt vmcnt(20)
	ds_write_b128 v169, v[28:31] offset:12288
	s_waitcnt vmcnt(19)
	ds_write_b128 v169, v[98:101] offset:16384
	s_waitcnt vmcnt(18)
	ds_write_b128 v169, v[102:105] offset:20480
	s_waitcnt vmcnt(17)
	ds_write_b128 v169, v[106:109] offset:24576
	s_waitcnt vmcnt(16)
	ds_write_b128 v169, v[110:113] offset:28672
	v_mov_b32_e32 v16, v2
	v_mov_b32_e32 v17, v2
	v_mov_b32_e32 v18, v2
	v_mov_b32_e32 v19, v2
	v_mov_b32_e32 v20, v2
	v_mov_b32_e32 v21, v2
	v_mov_b32_e32 v22, v2
	v_mov_b32_e32 v23, v2
	v_mov_b32_e32 v24, v2
	v_mov_b32_e32 v25, v2
	v_mov_b32_e32 v26, v2
	v_mov_b32_e32 v27, v2
	v_mov_b32_e32 v28, v2
	v_mov_b32_e32 v29, v2
	v_mov_b32_e32 v30, v2
	v_mov_b32_e32 v31, v2
	v_mov_b32_e32 v98, v2
	v_mov_b32_e32 v99, v2
	v_mov_b32_e32 v100, v2
	v_mov_b32_e32 v101, v2
	v_mov_b32_e32 v102, v2
	v_mov_b32_e32 v103, v2
	v_mov_b32_e32 v104, v2
	v_mov_b32_e32 v105, v2
	v_mov_b32_e32 v106, v2
	v_mov_b32_e32 v107, v2
	v_mov_b32_e32 v108, v2
	v_mov_b32_e32 v109, v2
	v_mov_b32_e32 v110, v2
	v_mov_b32_e32 v111, v2
	v_mov_b32_e32 v112, v2
	v_mov_b32_e32 v113, v2
	s_waitcnt lgkmcnt(0)
	s_barrier
.LBB0_1186:
	ds_read_b128 v[208:211], v192 offset:16384
	ds_read_b128 v[212:215], v192 offset:18432
	ds_read_b128 v[216:219], v192 offset:20480
	ds_read_b128 v[220:223], v192 offset:22528
	s_add_i32 s10, s9, 0xc0
	ds_read_b128 v[196:199], v170
	ds_read_b128 v[200:203], v170 offset:2048
	s_cmpk_lt_u32 s9, 0x340
	s_cselect_b32 s42, s10, 0x3c0
	ds_read_b128 v[204:207], v170 offset:4096
	s_lshl_b64 s[10:11], s[42:43], 1
	v_lshl_add_u64 v[160:161], v[154:155], 0, s[10:11]
	ds_read_b128 v[130:133], v170 offset:6144
	ds_read_b128 v[244:247], v243 offset:16384
	ds_read_b128 v[248:251], v243 offset:18432
	ds_read_b128 v[252:255], v243 offset:20480
	s_waitcnt lgkmcnt(6)
	v_mfma_f32_16x16x32_f16 v[126:129], v[208:211], v[196:199], v[126:129]
	v_lshl_add_u64 v[158:159], v[156:157], 0, s[10:11]
	s_add_i32 s10, s9, 0x100
	s_cmpk_lt_u32 s9, 0x300
	v_mfma_f32_16x16x32_f16 v[122:125], v[212:215], v[196:199], v[122:125]
	s_cselect_b32 s42, s10, 0x3c0
	s_lshl_b64 s[10:11], s[42:43], 1
	v_mfma_f32_16x16x32_f16 v[118:121], v[216:219], v[196:199], v[118:121]
	v_mfma_f32_16x16x32_f16 v[114:117], v[220:223], v[196:199], v[114:117]
	ds_read_b128 v[196:199], v243 offset:22528
	s_waitcnt vmcnt(15)
	ds_write_b128 v169, v[34:37] offset:32768
	global_load_dwordx4 v[34:37], v[160:161], off
	s_waitcnt lgkmcnt(7)
	v_mfma_f32_16x16x32_f16 v[110:113], v[208:211], v[200:203], v[110:113]
	v_mfma_f32_16x16x32_f16 v[106:109], v[212:215], v[200:203], v[106:109]
	v_mfma_f32_16x16x32_f16 v[102:105], v[216:219], v[200:203], v[102:105]
	v_mfma_f32_16x16x32_f16 v[98:101], v[220:223], v[200:203], v[98:101]
	ds_read_b128 v[200:203], v242
	s_waitcnt vmcnt(15)
	ds_write_b128 v169, v[42:45] offset:36864
	v_add_co_u32_e32 v42, vcc, s94, v160
	s_nop 1
	v_addc_co_u32_e32 v43, vcc, 0, v161, vcc
	global_load_dwordx4 v[42:45], v[42:43], off
	s_waitcnt lgkmcnt(8)
	v_mfma_f32_16x16x32_f16 v[30:33], v[208:211], v[204:207], v[30:33]
	v_mfma_f32_16x16x32_f16 v[26:29], v[212:215], v[204:207], v[26:29]
	v_mfma_f32_16x16x32_f16 v[22:25], v[216:219], v[204:207], v[22:25]
	v_mfma_f32_16x16x32_f16 v[18:21], v[220:223], v[204:207], v[18:21]
	ds_read_b128 v[204:207], v242 offset:2048
	s_waitcnt vmcnt(15)
	ds_write_b128 v169, v[46:49] offset:40960
	v_add_co_u32_e32 v46, vcc, s72, v160
	s_nop 1
	v_addc_co_u32_e32 v47, vcc, 0, v161, vcc
	global_load_dwordx4 v[46:49], v[46:47], off
	s_waitcnt lgkmcnt(9)
	v_mfma_f32_16x16x32_f16 v[14:17], v[208:211], v[130:133], v[14:17]
	v_mfma_f32_16x16x32_f16 v[10:13], v[212:215], v[130:133], v[10:13]
	v_mfma_f32_16x16x32_f16 v[6:9], v[216:219], v[130:133], v[6:9]
	v_mfma_f32_16x16x32_f16 v[2:5], v[220:223], v[130:133], v[2:5]
	ds_read_b128 v[130:133], v242 offset:4096
	ds_read_b128 v[208:211], v242 offset:6144
	s_waitcnt vmcnt(15)
	ds_write_b128 v169, v[50:53] offset:45056
	v_add_co_u32_e32 v50, vcc, s73, v160
	s_nop 1
	v_addc_co_u32_e32 v51, vcc, 0, v161, vcc
	global_load_dwordx4 v[50:53], v[50:51], off
	s_waitcnt lgkmcnt(6)
	v_mfma_f32_16x16x32_f16 v[126:129], v[244:247], v[200:203], v[126:129]
	v_mfma_f32_16x16x32_f16 v[122:125], v[248:251], v[200:203], v[122:125]
	v_mfma_f32_16x16x32_f16 v[118:121], v[252:255], v[200:203], v[118:121]
	v_mfma_f32_16x16x32_f16 v[114:117], v[196:199], v[200:203], v[114:117]
	s_waitcnt vmcnt(15)
	ds_write_b128 v169, v[38:41] offset:49152
	global_load_dwordx4 v[38:41], v[158:159], off
	v_lshl_add_u64 v[222:223], v[154:155], 0, s[10:11]
	s_waitcnt lgkmcnt(5)
	v_mfma_f32_16x16x32_f16 v[110:113], v[244:247], v[204:207], v[110:113]
	v_lshl_add_u64 v[220:221], v[156:157], 0, s[10:11]
	s_add_i32 s10, s9, 0x80
	s_cmpk_lt_u32 s9, 0x380
	v_mfma_f32_16x16x32_f16 v[106:109], v[248:251], v[204:207], v[106:109]
	s_mov_b32 s9, s10
	v_mfma_f32_16x16x32_f16 v[102:105], v[252:255], v[204:207], v[102:105]
	v_mfma_f32_16x16x32_f16 v[98:101], v[196:199], v[204:207], v[98:101]
	s_waitcnt vmcnt(15)
	ds_write_b128 v169, v[54:57] offset:53248
	v_add_co_u32_e32 v54, vcc, s94, v158
	s_nop 1
	v_addc_co_u32_e32 v55, vcc, 0, v159, vcc
	global_load_dwordx4 v[54:57], v[54:55], off
	s_waitcnt lgkmcnt(4)
	v_mfma_f32_16x16x32_f16 v[30:33], v[244:247], v[130:133], v[30:33]
	v_mfma_f32_16x16x32_f16 v[26:29], v[248:251], v[130:133], v[26:29]
	v_mfma_f32_16x16x32_f16 v[22:25], v[252:255], v[130:133], v[22:25]
	v_mfma_f32_16x16x32_f16 v[18:21], v[196:199], v[130:133], v[18:21]
	s_waitcnt vmcnt(15)
	ds_write_b128 v169, v[62:65] offset:57344
	v_add_co_u32_e32 v62, vcc, s72, v158
	s_nop 1
	v_addc_co_u32_e32 v63, vcc, 0, v159, vcc
	global_load_dwordx4 v[62:65], v[62:63], off
	s_waitcnt lgkmcnt(4)
	v_mfma_f32_16x16x32_f16 v[14:17], v[244:247], v[208:211], v[14:17]
	v_mfma_f32_16x16x32_f16 v[10:13], v[248:251], v[208:211], v[10:13]
	v_mfma_f32_16x16x32_f16 v[6:9], v[252:255], v[208:211], v[6:9]
	v_mfma_f32_16x16x32_f16 v[2:5], v[196:199], v[208:211], v[2:5]
	s_waitcnt vmcnt(15)
	ds_write_b128 v169, v[66:69] offset:61440
	v_add_co_u32_e32 v66, vcc, s73, v158
	s_nop 1
	v_addc_co_u32_e32 v67, vcc, 0, v159, vcc
	global_load_dwordx4 v[66:69], v[66:67], off
	s_waitcnt lgkmcnt(0)
	s_barrier
; template <int NJ>
; __device__ __forceinline__ void gemm_tile(const f16* __restrict__ A, int lda, const f16* __restrict__ Bt, int ldb,
;                                           int K, f32x4 (&acc)[4][NJ], f16* sA, f16* sB, const int tid) {
;     ...
;   for (int k0 = 0; k0 < K; k0 += 128) {
;     {
;       const int kof = (k0 + 192 < K) ? k0 + 192 : K - 64;
;       G_STEP(0, ra1, rb1, true, true, kof)
;     }
;     __syncthreads();
;     if (k0 + 64 >= K) break;
;     {
;       const int kof = (k0 + 256 < K) ? k0 + 256 : K - 64;
;       G_STEP(1, ra0, rb0, true, true, kof)
;     }
;     __syncthreads();
;   }
; template <int NJ>
; __device__ __forceinline__ void gres_tile(const Params& p, const f16* A, int lda, const f16* W, int K, const float* mod,
;                                           bool first_in, f16* sA, f16* sB, int m0, int n0) {
;     ...
;   for (int i = 0; i < 4; ++i) {
;     int m = m0 + wm * 64 + i * 16 + (lane & 15);
;     const float* xi = xrow_in(p, first_in ? 0 : 1, m);
;     float* xo = xrow_out(p, m);
;     const float* gt = mod + (size_t)modrow_of(m) * 6 * DM;
; #pragma unroll
;     for (int j = 0; j < NJ; ++j) {
;       int n = n0 + wn * (NJ * 16) + j * 16 + 4 * (lane >> 4);
;       float4 xv = *(const float4*)(xi + n);
	ds_read_b128 v[204:207], v192 offset:49152
	ds_read_b128 v[208:211], v192 offset:51200
	ds_read_b128 v[212:215], v192 offset:53248
	ds_read_b128 v[216:219], v192 offset:55296
	ds_read_b128 v[130:133], v170 offset:32768
	ds_read_b128 v[158:161], v170 offset:34816
	ds_read_b128 v[196:199], v170 offset:36864
	ds_read_b128 v[200:203], v170 offset:38912
	ds_read_b128 v[244:247], v243 offset:49152
	ds_read_b128 v[248:251], v243 offset:51200
	ds_read_b128 v[252:255], v243 offset:53248
	s_waitcnt lgkmcnt(6)
	v_mfma_f32_16x16x32_f16 v[126:129], v[204:207], v[130:133], v[126:129]
	v_mfma_f32_16x16x32_f16 v[122:125], v[208:211], v[130:133], v[122:125]
	v_mfma_f32_16x16x32_f16 v[118:121], v[212:215], v[130:133], v[118:121]
	v_mfma_f32_16x16x32_f16 v[114:117], v[216:219], v[130:133], v[114:117]
	ds_read_b128 v[130:133], v243 offset:55296
	s_waitcnt vmcnt(13)
	ds_write_b128 v169, v[58:61]
	global_load_dwordx4 v[58:61], v[222:223], off
	s_waitcnt lgkmcnt(7)
	v_mfma_f32_16x16x32_f16 v[110:113], v[204:207], v[158:161], v[110:113]
	v_mfma_f32_16x16x32_f16 v[106:109], v[208:211], v[158:161], v[106:109]
	v_mfma_f32_16x16x32_f16 v[102:105], v[212:215], v[158:161], v[102:105]
	v_mfma_f32_16x16x32_f16 v[98:101], v[216:219], v[158:161], v[98:101]
	ds_read_b128 v[158:161], v242 offset:32768
	ds_write_b128 v169, v[74:77] offset:4096
	v_add_co_u32_e32 v74, vcc, s94, v222
	s_nop 1
	v_addc_co_u32_e32 v75, vcc, 0, v223, vcc
	global_load_dwordx4 v[74:77], v[74:75], off
	s_waitcnt lgkmcnt(8)
	v_mfma_f32_16x16x32_f16 v[30:33], v[204:207], v[196:199], v[30:33]
	v_mfma_f32_16x16x32_f16 v[26:29], v[208:211], v[196:199], v[26:29]
	v_mfma_f32_16x16x32_f16 v[22:25], v[212:215], v[196:199], v[22:25]
	v_mfma_f32_16x16x32_f16 v[18:21], v[216:219], v[196:199], v[18:21]
	ds_read_b128 v[196:199], v242 offset:34816
	ds_write_b128 v169, v[78:81] offset:8192
	v_add_co_u32_e32 v78, vcc, s72, v222
	s_nop 1
	v_addc_co_u32_e32 v79, vcc, 0, v223, vcc
	global_load_dwordx4 v[78:81], v[78:79], off
	s_waitcnt lgkmcnt(9)
	v_mfma_f32_16x16x32_f16 v[14:17], v[204:207], v[200:203], v[14:17]
	v_mfma_f32_16x16x32_f16 v[10:13], v[208:211], v[200:203], v[10:13]
	v_mfma_f32_16x16x32_f16 v[6:9], v[212:215], v[200:203], v[6:9]
	v_mfma_f32_16x16x32_f16 v[2:5], v[216:219], v[200:203], v[2:5]
	ds_read_b128 v[200:203], v242 offset:36864
	ds_read_b128 v[204:207], v242 offset:38912
	s_waitcnt vmcnt(14)
	ds_write_b128 v169, v[82:85] offset:12288
	v_add_co_u32_e32 v82, vcc, s73, v222
	s_nop 1
	v_addc_co_u32_e32 v83, vcc, 0, v223, vcc
	global_load_dwordx4 v[82:85], v[82:83], off
	s_waitcnt lgkmcnt(6)
	v_mfma_f32_16x16x32_f16 v[126:129], v[244:247], v[158:161], v[126:129]
	v_mfma_f32_16x16x32_f16 v[122:125], v[248:251], v[158:161], v[122:125]
	v_mfma_f32_16x16x32_f16 v[118:121], v[252:255], v[158:161], v[118:121]
	v_mfma_f32_16x16x32_f16 v[114:117], v[130:133], v[158:161], v[114:117]
	ds_write_b128 v169, v[70:73] offset:16384
	global_load_dwordx4 v[70:73], v[220:221], off
	s_waitcnt lgkmcnt(5)
	v_mfma_f32_16x16x32_f16 v[110:113], v[244:247], v[196:199], v[110:113]
	v_mfma_f32_16x16x32_f16 v[106:109], v[248:251], v[196:199], v[106:109]
	v_mfma_f32_16x16x32_f16 v[102:105], v[252:255], v[196:199], v[102:105]
	v_mfma_f32_16x16x32_f16 v[98:101], v[130:133], v[196:199], v[98:101]
	s_waitcnt vmcnt(15)
	ds_write_b128 v169, v[86:89] offset:20480
	v_add_co_u32_e32 v86, vcc, s94, v220
	s_nop 1
	v_addc_co_u32_e32 v87, vcc, 0, v221, vcc
	global_load_dwordx4 v[86:89], v[86:87], off
	s_waitcnt lgkmcnt(4)
	v_mfma_f32_16x16x32_f16 v[30:33], v[244:247], v[200:203], v[30:33]
	v_mfma_f32_16x16x32_f16 v[26:29], v[248:251], v[200:203], v[26:29]
	v_mfma_f32_16x16x32_f16 v[22:25], v[252:255], v[200:203], v[22:25]
	v_mfma_f32_16x16x32_f16 v[18:21], v[130:133], v[200:203], v[18:21]
	s_waitcnt vmcnt(15)
	ds_write_b128 v169, v[90:93] offset:24576
	v_add_co_u32_e32 v90, vcc, s72, v220
	s_nop 1
	v_addc_co_u32_e32 v91, vcc, 0, v221, vcc
	global_load_dwordx4 v[90:93], v[90:91], off
	s_waitcnt lgkmcnt(4)
	v_mfma_f32_16x16x32_f16 v[14:17], v[244:247], v[204:207], v[14:17]
	v_mfma_f32_16x16x32_f16 v[10:13], v[248:251], v[204:207], v[10:13]
	v_mfma_f32_16x16x32_f16 v[6:9], v[252:255], v[204:207], v[6:9]
	v_mfma_f32_16x16x32_f16 v[2:5], v[130:133], v[204:207], v[2:5]
	s_waitcnt vmcnt(15)
	ds_write_b128 v169, v[94:97] offset:28672
	v_add_co_u32_e32 v94, vcc, s73, v220
	s_nop 1
	v_addc_co_u32_e32 v95, vcc, 0, v221, vcc
	global_load_dwordx4 v[94:97], v[94:95], off
	s_waitcnt lgkmcnt(0)
	s_barrier
	s_cbranch_scc1 .LBB0_1186
	s_waitcnt vmcnt(15)
	v_or_b32_e32 v34, s8, v162
	v_add_u32_e32 v34, v34, v147
	v_cmp_gt_i32_e64 s[8:9], s80, v34
	v_cmp_lt_i32_e64 s[10:11], s82, v34
	s_mov_b64 s[14:15], -1
	s_and_b64 vcc, exec, s[30:31]
	s_cbranch_vccz .LBB0_1193
	v_mov_b64_e32 v[36:37], v[0:1]
	s_and_saveexec_b64 s[14:15], s[10:11]
	s_xor_b64 s[14:15], exec, s[14:15]
	s_cbranch_execz .LBB0_1190
	v_add_u32_e32 v164, 0xffff8000, v34
	v_mov_b64_e32 v[36:37], v[152:153]
	s_waitcnt vmcnt(11)
	v_mov_b64_e32 v[38:39], v[164:165]

; template <int NJ>
; __device__ __forceinline__ void gemm_tile(const f16* __restrict__ A, int lda, const f16* __restrict__ Bt, int ldb,
;                                           int K, f32x4 (&acc)[4][NJ], f16* sA, f16* sB, const int tid) {
;     ...
;   const int crow = tid >> 3, ckc = (tid & 7) * 8;
;   const f16* ap = A + (size_t)crow * lda + ckc;
;   const f16* bp = Bt + (size_t)crow * ldb + ckc;
;   const int woff = crow * LDT + ckc;
;   const int aoff = (wm * 64 + (lane & 15)) * LDT + (lane >> 4) * 8;
;   const int boff = (wn * (NJ * 16) + (lane & 15)) * LDT + (lane >> 4) * 8;
; __device__ __forceinline__ void phase_gres(const Params& p, int l, const f16* A, int lda, const f16* W, int K, int gate_idx,
;                            bool first_in, f16* smem) {
;     ...
;   for (int u = blockIdx.x; u < 2 * (MT * NT - full); u += gridDim.x) {
;     const int t = full + (u >> 1);
;     gres_tile<2>(p, A, lda, W, K, mod, first_in, sA, sB, (t / NT) * 128, (t % NT) * 128 + (u & 1) * 64);
.LBB0_1234:
	v_readlane_b32 s10, v241, 34
	v_readlane_b32 s11, v241, 35
	s_andn2_b64 vcc, exec, s[10:11]
	s_nop 0
	v_cndmask_b32_e64 v2, 0, 1, s[10:11]
	v_cmp_ne_u32_e64 s[8:9], 1, v2
	s_cbranch_vccnz .LBB0_1287
	s_cmp_eq_u32 s4, 3
	s_cbranch_scc1 .LBB0_1287
	v_ashrrev_i32_e32 v147, 31, v146
	v_and_b32_e32 v6, 56, v168
	v_lshlrev_b64 v[2:3], 11, v[146:147]
	v_lshl_add_u64 v[4:5], v[144:145], 0, v[2:3]
	v_lshlrev_b32_e32 v164, 1, v6
	v_and_b32_e32 v92, 0xffffffc0, v167
	v_and_b32_e32 v8, 32, v166
	v_lshl_add_u64 v[82:83], v[4:5], 0, v[164:165]
	v_lshl_add_u64 v[2:3], v[142:143], 0, v[2:3]
	s_movk_i32 s5, 0x48
	v_or_b32_e32 v5, v92, v162
	v_or_b32_e32 v9, v8, v162
	v_mul_lo_u32 v4, v146, s5
	v_and_b32_e32 v7, 24, v166
	v_mul_u32_u24_e32 v9, 0x48, v9
	v_lshl_add_u64 v[84:85], v[2:3], 0, v[164:165]
	v_mul_lo_u32 v2, v5, s5
	v_add_lshl_u32 v93, v4, v6, 1
	v_add_lshl_u32 v94, v2, v7, 1
	v_add_lshl_u32 v95, v9, v7, 1
	v_and_or_b32 v96, v163, 12, v8
	v_lshrrev_b32_e32 v242, 3, v171
	v_xor_b32_e32 v243, v242, v171
	v_and_b32_e32 v243, 7, v243
	v_lshlrev_b32_e32 v243, 4, v243
	v_lshl_or_b32 v93, v242, 7, v243
	v_bfe_u32 v242, v171, 4, 2
	v_xor_b32_e32 v242, v242, v171
	v_and_b32_e32 v242, 7, v242
	v_lshlrev_b32_e32 v242, 4, v242
	v_lshrrev_b32_e32 v243, 1, v171
	v_and_b32_e32 v243, 64, v243
	v_and_or_b32 v243, v171, 15, v243
	v_lshl_or_b32 v94, v243, 7, v242
	v_lshrrev_b32_e32 v243, 1, v171
	v_and_b32_e32 v243, 32, v243
	v_and_or_b32 v243, v171, 15, v243
	v_lshl_or_b32 v95, v243, 7, v242
	v_xor_b32_e32 v242, 64, v94
	v_xor_b32_e32 v243, 64, v95
	s_mov_b32 s5, s95
	s_branch .LBB0_1238

; __device__ __forceinline__ void phase_g4(const Params& p, f16* smem) {
;     ...
;   for (int t = blockIdx.x; t < MT * NT; t += gridDim.x) {
;     int m0 = (t / NT) * 128, nt = t % NT;
.LBB0_1397:
	s_cmpk_lg_u32 s26, 0x200
	s_cbranch_scc1 .Lxm_orig_g4
	s_cmpk_ge_u32 s5, 0x2c00
	s_cbranch_scc1 .Lxm_last_g4
	s_and_b32 s14, s5, 7
	s_mul_i32 s14, s14, 22
	s_lshr_b32 s15, s5, 9
	s_add_i32 s14, s14, s15
	s_lshl_b32 s14, s14, 6
	s_bfe_u32 s15, s5, 0x60003
	s_or_b32 s14, s14, s15
	s_mul_i32 s15, s14, 2979
	s_lshr_b32 s15, s15, 20
	s_mul_i32 s16, s15, 352
	s_sub_i32 s16, s14, s16
	s_lshr_b32 s12, s16, 3
	s_and_b32 s16, s16, 7
	s_lshl_b32 s15, s15, 3
	s_add_i32 s11, s15, s16
	s_branch .Lxm_fin_g4
.Lxm_last_g4:
	s_sub_i32 s16, s5, 0x2c00
	s_lshr_b32 s12, s16, 2
	s_and_b32 s16, s16, 3
	s_add_i32 s11, s16, 0x100
.Lxm_fin_g4:
	s_lshl_b32 s10, s11, 7
	s_branch .Lxm_done_g4

; template <int NJ>
; __device__ __forceinline__ void gemm_tile(const f16* __restrict__ A, int lda, const f16* __restrict__ Bt, int ldb,
;                                           int K, f32x4 (&acc)[4][NJ], f16* sA, f16* sB, const int tid) {
;     ...
;   G_LOAD(ra0, rb0, 0)
;   if (K > 64) G_LOAD(ra1, rb1, 64)
;   __syncthreads();
;   G_STORE(ra0, rb0, 0)
;   if (K > 128) G_LOAD(ra0, rb0, 128)
;   __syncthreads();
; #pragma unroll 1
;   for (int k0 = 0; k0 < K; k0 += 128) {
;     {
;       const int kof = (k0 + 192 < K) ? k0 + 192 : K - 64;
;       G_STEP(0, ra1, rb1, true, true, kof)
.Lxm_done_g4:
	s_ashr_i32 s11, s10, 31
	s_lshl_b64 s[14:15], s[10:11], 11
	v_lshl_add_u64 v[138:139], v[134:135], 0, s[14:15]
	v_add_co_u32_e32 v0, vcc, s94, v138
	s_ashr_i32 s13, s12, 31
	s_nop 0
	v_addc_co_u32_e32 v1, vcc, 0, v139, vcc
	v_add_co_u32_e32 v2, vcc, s72, v138
	s_lshl_b64 s[16:17], s[12:13], 18
	s_nop 0
	v_addc_co_u32_e32 v3, vcc, 0, v139, vcc
	v_add_co_u32_e32 v4, vcc, s73, v138
	v_lshl_add_u64 v[140:141], v[136:137], 0, s[16:17]
	s_nop 0
	v_addc_co_u32_e32 v5, vcc, 0, v139, vcc
	v_add_co_u32_e32 v6, vcc, s94, v140
	global_load_dwordx4 v[14:17], v[138:139], off
	s_nop 0
	v_addc_co_u32_e32 v7, vcc, 0, v141, vcc
	v_add_co_u32_e32 v8, vcc, s72, v140
	global_load_dwordx4 v[18:21], v[0:1], off
	s_nop 0
	v_addc_co_u32_e32 v9, vcc, 0, v141, vcc
	v_add_co_u32_e32 v10, vcc, s73, v140
	global_load_dwordx4 v[22:25], v[2:3], off
	s_nop 0
	v_addc_co_u32_e32 v11, vcc, 0, v141, vcc
	global_load_dwordx4 v[26:29], v[4:5], off
	global_load_dwordx4 v[30:33], v[140:141], off
	global_load_dwordx4 v[34:37], v[6:7], off
	global_load_dwordx4 v[104:107], v[8:9], off
	global_load_dwordx4 v[108:111], v[10:11], off
	global_load_dwordx4 v[40:43], v[138:139], off offset:128
	global_load_dwordx4 v[44:47], v[140:141], off offset:128
	global_load_dwordx4 v[48:51], v[0:1], off offset:128
	global_load_dwordx4 v[52:55], v[2:3], off offset:128
	global_load_dwordx4 v[56:59], v[4:5], off offset:128
	global_load_dwordx4 v[60:63], v[6:7], off offset:128
	global_load_dwordx4 v[68:71], v[8:9], off offset:128
	global_load_dwordx4 v[72:75], v[10:11], off offset:128
	s_barrier
	global_load_dwordx4 v[80:83], v[0:1], off offset:256
	global_load_dwordx4 v[84:87], v[2:3], off offset:256
	global_load_dwordx4 v[64:67], v[138:139], off offset:256
	global_load_dwordx4 v[76:79], v[140:141], off offset:256
	global_load_dwordx4 v[88:91], v[4:5], off offset:256
	global_load_dwordx4 v[92:95], v[6:7], off offset:256
	global_load_dwordx4 v[96:99], v[8:9], off offset:256
	global_load_dwordx4 v[100:103], v[10:11], off offset:256
	v_mov_b32_e32 v0, 0
	s_mov_b32 s11, 0
	v_mov_b32_e32 v1, v0
	v_mov_b32_e32 v2, v0
	v_mov_b32_e32 v3, v0
	v_mov_b32_e32 v8, v0
	v_mov_b32_e32 v9, v0
	v_mov_b32_e32 v10, v0
	v_mov_b32_e32 v11, v0
	v_mov_b32_e32 v4, v0
	v_mov_b32_e32 v5, v0
	v_mov_b32_e32 v6, v0
	v_mov_b32_e32 v7, v0
	v_mov_b32_e32 v12, v0
	v_mov_b32_e32 v13, v0
	v_mov_b32_e32 v38, v0
	v_mov_b32_e32 v39, v0
	v_mov_b32_e32 v112, v0
	v_mov_b32_e32 v113, v0
	v_mov_b32_e32 v114, v0
	v_mov_b32_e32 v115, v0
	v_mov_b32_e32 v120, v0
	v_mov_b32_e32 v121, v0
	v_mov_b32_e32 v122, v0
	v_mov_b32_e32 v123, v0
	v_mov_b32_e32 v116, v0
	v_mov_b32_e32 v117, v0
	v_mov_b32_e32 v118, v0
	v_mov_b32_e32 v119, v0
	v_mov_b32_e32 v124, v0
	v_mov_b32_e32 v125, v0
	v_mov_b32_e32 v126, v0
	v_mov_b32_e32 v127, v0
	s_waitcnt vmcnt(23)
	ds_write_b128 v147, v[14:17]
	s_waitcnt vmcnt(19)
	ds_write_b128 v147, v[30:33] offset:16384
	ds_write_b128 v147, v[18:21] offset:4096
	ds_write_b128 v147, v[22:25] offset:8192
	ds_write_b128 v147, v[26:29] offset:12288
	s_waitcnt vmcnt(18)
	ds_write_b128 v147, v[34:37] offset:20480
	s_waitcnt vmcnt(17)
	ds_write_b128 v147, v[104:107] offset:24576
	s_waitcnt vmcnt(16)
	ds_write_b128 v147, v[108:111] offset:28672
	v_mov_b32_e32 v14, v0
	v_mov_b32_e32 v15, v0
	v_mov_b32_e32 v16, v0
	v_mov_b32_e32 v17, v0
	v_mov_b32_e32 v18, v0
	v_mov_b32_e32 v19, v0
	v_mov_b32_e32 v24, v0
	v_mov_b32_e32 v25, v0
	v_mov_b32_e32 v26, v0
	v_mov_b32_e32 v27, v0
	v_mov_b32_e32 v20, v0
	v_mov_b32_e32 v21, v0
	v_mov_b32_e32 v22, v0
	v_mov_b32_e32 v23, v0
	v_mov_b32_e32 v28, v0
	v_mov_b32_e32 v29, v0
	v_mov_b32_e32 v30, v0
	v_mov_b32_e32 v31, v0
	v_mov_b32_e32 v32, v0
	v_mov_b32_e32 v33, v0
	v_mov_b32_e32 v34, v0
	v_mov_b32_e32 v35, v0
	v_mov_b32_e32 v104, v0
	v_mov_b32_e32 v105, v0
	v_mov_b32_e32 v106, v0
	v_mov_b32_e32 v107, v0
	v_mov_b32_e32 v36, v0
	v_mov_b32_e32 v37, v0
	v_mov_b32_e32 v108, v0
	v_mov_b32_e32 v109, v0
	v_mov_b32_e32 v110, v0
	v_mov_b32_e32 v111, v0
	s_waitcnt lgkmcnt(0)
	s_barrier
.LBB0_1398:
	ds_read_b128 v[166:169], v148 offset:16384
	ds_read_b128 v[192:195], v148 offset:18432
	ds_read_b128 v[196:199], v148 offset:20480
	ds_read_b128 v[200:203], v148 offset:22528
	s_add_i32 s13, s11, 0xc0
	ds_read_b128 v[152:155], v150
	ds_read_b128 v[156:159], v150 offset:2048
	s_cmpk_lt_u32 s11, 0x340
	s_cselect_b32 s42, s13, 0x3c0
	ds_read_b128 v[160:163], v150 offset:4096
	s_lshl_b64 s[14:15], s[42:43], 1
	v_lshl_add_u64 v[144:145], v[138:139], 0, s[14:15]
	ds_read_b128 v[128:131], v150 offset:6144
	ds_read_b128 v[244:247], v243 offset:16384
	ds_read_b128 v[248:251], v243 offset:18432
	ds_read_b128 v[252:255], v243 offset:20480
	s_waitcnt lgkmcnt(6)
	v_mfma_f32_16x16x32_f16 v[124:127], v[166:169], v[152:155], v[124:127]
	v_lshl_add_u64 v[142:143], v[140:141], 0, s[14:15]
	s_add_i32 s13, s11, 0x100
	s_cmpk_lt_u32 s11, 0x300
	v_mfma_f32_16x16x32_f16 v[116:119], v[192:195], v[152:155], v[116:119]
	s_cselect_b32 s42, s13, 0x3c0
	s_lshl_b64 s[14:15], s[42:43], 1
	s_add_i32 s13, s11, 0x80
	v_mfma_f32_16x16x32_f16 v[120:123], v[196:199], v[152:155], v[120:123]
	s_cmpk_lt_u32 s11, 0x380
	s_mov_b32 s11, s13
	v_mfma_f32_16x16x32_f16 v[112:115], v[200:203], v[152:155], v[112:115]
	ds_read_b128 v[152:155], v243 offset:22528
	s_waitcnt vmcnt(15)
	ds_write_b128 v147, v[40:43] offset:32768
	global_load_dwordx4 v[40:43], v[144:145], off
	s_waitcnt lgkmcnt(7)
	v_mfma_f32_16x16x32_f16 v[108:111], v[166:169], v[156:159], v[108:111]
	v_mfma_f32_16x16x32_f16 v[36:39], v[192:195], v[156:159], v[36:39]
	v_mfma_f32_16x16x32_f16 v[104:107], v[196:199], v[156:159], v[104:107]
	v_mfma_f32_16x16x32_f16 v[32:35], v[200:203], v[156:159], v[32:35]
	ds_read_b128 v[156:159], v242
	s_waitcnt vmcnt(14)
	ds_write_b128 v147, v[48:51] offset:36864
	v_add_co_u32_e32 v48, vcc, s94, v144
	s_nop 1
	v_addc_co_u32_e32 v49, vcc, 0, v145, vcc
	global_load_dwordx4 v[48:51], v[48:49], off
	s_waitcnt lgkmcnt(8)
	v_mfma_f32_16x16x32_f16 v[28:31], v[166:169], v[160:163], v[28:31]
	v_mfma_f32_16x16x32_f16 v[20:23], v[192:195], v[160:163], v[20:23]
	v_mfma_f32_16x16x32_f16 v[24:27], v[196:199], v[160:163], v[24:27]
	v_mfma_f32_16x16x32_f16 v[16:19], v[200:203], v[160:163], v[16:19]
	ds_read_b128 v[160:163], v242 offset:2048
	s_waitcnt vmcnt(14)
	ds_write_b128 v147, v[52:55] offset:40960
	v_add_co_u32_e32 v52, vcc, s72, v144
	s_nop 1
	v_addc_co_u32_e32 v53, vcc, 0, v145, vcc
	global_load_dwordx4 v[52:55], v[52:53], off
	s_waitcnt lgkmcnt(9)
	v_mfma_f32_16x16x32_f16 v[12:15], v[166:169], v[128:131], v[12:15]
	v_mfma_f32_16x16x32_f16 v[4:7], v[192:195], v[128:131], v[4:7]
	v_mfma_f32_16x16x32_f16 v[8:11], v[196:199], v[128:131], v[8:11]
	v_mfma_f32_16x16x32_f16 v[0:3], v[200:203], v[128:131], v[0:3]
	ds_read_b128 v[128:131], v242 offset:4096
	ds_read_b128 v[166:169], v242 offset:6144
	s_waitcnt vmcnt(14)
	ds_write_b128 v147, v[56:59] offset:45056
	v_add_co_u32_e32 v56, vcc, s73, v144
	s_nop 1
	v_addc_co_u32_e32 v57, vcc, 0, v145, vcc
	global_load_dwordx4 v[56:59], v[56:57], off
	s_waitcnt lgkmcnt(6)
	v_mfma_f32_16x16x32_f16 v[124:127], v[244:247], v[156:159], v[124:127]
	v_mfma_f32_16x16x32_f16 v[116:119], v[248:251], v[156:159], v[116:119]
	v_mfma_f32_16x16x32_f16 v[120:123], v[252:255], v[156:159], v[120:123]
	v_mfma_f32_16x16x32_f16 v[112:115], v[152:155], v[156:159], v[112:115]
	ds_write_b128 v147, v[44:47] offset:49152
	global_load_dwordx4 v[44:47], v[142:143], off
	v_lshl_add_u64 v[202:203], v[138:139], 0, s[14:15]
	s_waitcnt lgkmcnt(5)
	v_mfma_f32_16x16x32_f16 v[108:111], v[244:247], v[160:163], v[108:111]
	v_lshl_add_u64 v[200:201], v[140:141], 0, s[14:15]
	v_mfma_f32_16x16x32_f16 v[36:39], v[248:251], v[160:163], v[36:39]
	v_mfma_f32_16x16x32_f16 v[104:107], v[252:255], v[160:163], v[104:107]
	v_mfma_f32_16x16x32_f16 v[32:35], v[152:155], v[160:163], v[32:35]
	s_waitcnt vmcnt(15)
	ds_write_b128 v147, v[60:63] offset:53248
	v_add_co_u32_e32 v60, vcc, s94, v142
	s_nop 1
	v_addc_co_u32_e32 v61, vcc, 0, v143, vcc
	global_load_dwordx4 v[60:63], v[60:61], off
	s_waitcnt lgkmcnt(4)
	v_mfma_f32_16x16x32_f16 v[28:31], v[244:247], v[128:131], v[28:31]
	v_mfma_f32_16x16x32_f16 v[20:23], v[248:251], v[128:131], v[20:23]
	v_mfma_f32_16x16x32_f16 v[24:27], v[252:255], v[128:131], v[24:27]
	v_mfma_f32_16x16x32_f16 v[16:19], v[152:155], v[128:131], v[16:19]
	s_waitcnt vmcnt(15)
	ds_write_b128 v147, v[68:71] offset:57344
	v_add_co_u32_e32 v68, vcc, s72, v142
	s_nop 1
	v_addc_co_u32_e32 v69, vcc, 0, v143, vcc
	global_load_dwordx4 v[68:71], v[68:69], off
	s_waitcnt lgkmcnt(4)
	v_mfma_f32_16x16x32_f16 v[12:15], v[244:247], v[166:169], v[12:15]
	v_mfma_f32_16x16x32_f16 v[4:7], v[248:251], v[166:169], v[4:7]
	v_mfma_f32_16x16x32_f16 v[8:11], v[252:255], v[166:169], v[8:11]
	v_mfma_f32_16x16x32_f16 v[0:3], v[152:155], v[166:169], v[0:3]
	s_waitcnt vmcnt(15)
	ds_write_b128 v147, v[72:75] offset:61440
	v_add_co_u32_e32 v72, vcc, s73, v142
	s_nop 1
	v_addc_co_u32_e32 v73, vcc, 0, v143, vcc
	global_load_dwordx4 v[72:75], v[72:73], off
	s_waitcnt lgkmcnt(0)
	s_barrier
	ds_read_b128 v[160:163], v148 offset:49152
	ds_read_b128 v[166:169], v148 offset:51200
	ds_read_b128 v[192:195], v148 offset:53248
	ds_read_b128 v[196:199], v148 offset:55296
	ds_read_b128 v[128:131], v150 offset:32768
	ds_read_b128 v[142:145], v150 offset:34816
	ds_read_b128 v[152:155], v150 offset:36864
	ds_read_b128 v[156:159], v150 offset:38912
	ds_read_b128 v[244:247], v243 offset:49152
	ds_read_b128 v[248:251], v243 offset:51200
	ds_read_b128 v[252:255], v243 offset:53248
	s_waitcnt lgkmcnt(6)
	v_mfma_f32_16x16x32_f16 v[124:127], v[160:163], v[128:131], v[124:127]
	v_mfma_f32_16x16x32_f16 v[116:119], v[166:169], v[128:131], v[116:119]
	v_mfma_f32_16x16x32_f16 v[120:123], v[192:195], v[128:131], v[120:123]
	v_mfma_f32_16x16x32_f16 v[112:115], v[196:199], v[128:131], v[112:115]
	ds_read_b128 v[128:131], v243 offset:55296
	s_waitcnt vmcnt(13)
	ds_write_b128 v147, v[64:67]
	global_load_dwordx4 v[64:67], v[202:203], off
	s_waitcnt lgkmcnt(7)
	v_mfma_f32_16x16x32_f16 v[108:111], v[160:163], v[142:145], v[108:111]
	v_mfma_f32_16x16x32_f16 v[36:39], v[166:169], v[142:145], v[36:39]
	v_mfma_f32_16x16x32_f16 v[104:107], v[192:195], v[142:145], v[104:107]
	v_mfma_f32_16x16x32_f16 v[32:35], v[196:199], v[142:145], v[32:35]
	ds_read_b128 v[142:145], v242 offset:32768
	ds_write_b128 v147, v[80:83] offset:4096
	v_add_co_u32_e32 v80, vcc, s94, v202
	s_nop 1
	v_addc_co_u32_e32 v81, vcc, 0, v203, vcc
	global_load_dwordx4 v[80:83], v[80:81], off
	s_waitcnt lgkmcnt(8)
	v_mfma_f32_16x16x32_f16 v[28:31], v[160:163], v[152:155], v[28:31]
	v_mfma_f32_16x16x32_f16 v[20:23], v[166:169], v[152:155], v[20:23]
	v_mfma_f32_16x16x32_f16 v[24:27], v[192:195], v[152:155], v[24:27]
	v_mfma_f32_16x16x32_f16 v[16:19], v[196:199], v[152:155], v[16:19]
	ds_read_b128 v[152:155], v242 offset:34816
	ds_write_b128 v147, v[84:87] offset:8192
	v_add_co_u32_e32 v84, vcc, s72, v202
	s_nop 1
	v_addc_co_u32_e32 v85, vcc, 0, v203, vcc
	global_load_dwordx4 v[84:87], v[84:85], off
	s_waitcnt lgkmcnt(9)
	v_mfma_f32_16x16x32_f16 v[12:15], v[160:163], v[156:159], v[12:15]
	v_mfma_f32_16x16x32_f16 v[4:7], v[166:169], v[156:159], v[4:7]
	v_mfma_f32_16x16x32_f16 v[8:11], v[192:195], v[156:159], v[8:11]
	v_mfma_f32_16x16x32_f16 v[0:3], v[196:199], v[156:159], v[0:3]
	ds_read_b128 v[156:159], v242 offset:36864
	ds_read_b128 v[160:163], v242 offset:38912
	s_waitcnt vmcnt(14)
; __device__ __forceinline__ float siluf_(float x) { return x / (1.0f + __expf(-x)); }
; template <int NJ>
; __device__ __forceinline__ void gemm_tile(const f16* __restrict__ A, int lda, const f16* __restrict__ Bt, int ldb,
;                                           int K, f32x4 (&acc)[4][NJ], f16* sA, f16* sB, const int tid) {
;     ...
;     __syncthreads();
;     if (k0 + 64 >= K) break;
;     {
;       const int kof = (k0 + 256 < K) ? k0 + 256 : K - 64;
;       G_STEP(1, ra0, rb0, true, true, kof)
;     }
;     __syncthreads();
;   }
; __device__ __forceinline__ void phase_g4(const Params& p, f16* smem) {
;     ...
;     for (int i = 0; i < 4; ++i) {
;       int m = m0 + wm * 64 + i * 16 + (lane & 15);
; #pragma unroll
;       for (int jj = 0; jj < 2; ++jj) {
;         int u = nt * 64 + wn * 32 + jj * 16 + 4 * (lane >> 4);
;         f16x4 o;
; #pragma unroll
;         for (int r = 0; r < 4; ++r) o[r] = (f16)(siluf_(acc[i][jj][r]) * acc[i][jj + 2][r]);
;         *(f16x4*)(hid + (size_t)m * FF + u) = o;
	ds_write_b128 v147, v[88:91] offset:12288
	v_add_co_u32_e32 v88, vcc, s73, v202
	s_nop 1
	v_addc_co_u32_e32 v89, vcc, 0, v203, vcc
	global_load_dwordx4 v[88:91], v[88:89], off
	s_waitcnt lgkmcnt(6)
	v_mfma_f32_16x16x32_f16 v[124:127], v[244:247], v[142:145], v[124:127]
	v_mfma_f32_16x16x32_f16 v[116:119], v[248:251], v[142:145], v[116:119]
	v_mfma_f32_16x16x32_f16 v[120:123], v[252:255], v[142:145], v[120:123]
	v_mfma_f32_16x16x32_f16 v[112:115], v[128:131], v[142:145], v[112:115]
	ds_write_b128 v147, v[76:79] offset:16384
	global_load_dwordx4 v[76:79], v[200:201], off
	s_waitcnt lgkmcnt(5)
	v_mfma_f32_16x16x32_f16 v[108:111], v[244:247], v[152:155], v[108:111]
	v_mfma_f32_16x16x32_f16 v[36:39], v[248:251], v[152:155], v[36:39]
	v_mfma_f32_16x16x32_f16 v[104:107], v[252:255], v[152:155], v[104:107]
	v_mfma_f32_16x16x32_f16 v[32:35], v[128:131], v[152:155], v[32:35]
	s_waitcnt vmcnt(15)
	ds_write_b128 v147, v[92:95] offset:20480
	v_add_co_u32_e32 v92, vcc, s94, v200
	s_nop 1
	v_addc_co_u32_e32 v93, vcc, 0, v201, vcc
	global_load_dwordx4 v[92:95], v[92:93], off
	s_waitcnt lgkmcnt(4)
	v_mfma_f32_16x16x32_f16 v[28:31], v[244:247], v[156:159], v[28:31]
	v_mfma_f32_16x16x32_f16 v[20:23], v[248:251], v[156:159], v[20:23]
	v_mfma_f32_16x16x32_f16 v[24:27], v[252:255], v[156:159], v[24:27]
	v_mfma_f32_16x16x32_f16 v[16:19], v[128:131], v[156:159], v[16:19]
	s_waitcnt vmcnt(15)
	ds_write_b128 v147, v[96:99] offset:24576
	v_add_co_u32_e32 v96, vcc, s72, v200
	s_nop 1
	v_addc_co_u32_e32 v97, vcc, 0, v201, vcc
	global_load_dwordx4 v[96:99], v[96:97], off
	s_waitcnt lgkmcnt(4)
	v_mfma_f32_16x16x32_f16 v[12:15], v[244:247], v[160:163], v[12:15]
	v_mfma_f32_16x16x32_f16 v[4:7], v[248:251], v[160:163], v[4:7]
	v_mfma_f32_16x16x32_f16 v[8:11], v[252:255], v[160:163], v[8:11]
	v_mfma_f32_16x16x32_f16 v[0:3], v[128:131], v[160:163], v[0:3]
	s_waitcnt vmcnt(15)
	ds_write_b128 v147, v[100:103] offset:28672
	v_add_co_u32_e32 v100, vcc, s73, v200
	s_nop 1
	v_addc_co_u32_e32 v101, vcc, 0, v201, vcc
	global_load_dwordx4 v[100:103], v[100:101], off
	s_waitcnt lgkmcnt(0)
	s_barrier
	s_cbranch_scc1 .LBB0_1398
	s_waitcnt vmcnt(15)
	v_mul_f32_e32 v41, 0xbfb8aa3b, v124
	s_waitcnt vmcnt(11)
	v_exp_f32_e32 v46, v41
	v_mul_f32_e32 v41, 0xbfb8aa3b, v125
	v_exp_f32_e32 v47, v41
	v_add_u32_e32 v42, s10, v146
	v_lshl_or_b32 v40, s12, 6, v149
	v_mad_i64_i32 v[44:45], s[10:11], v42, s96, v[132:133]
	v_pk_add_f32 v[46:47], v[46:47], 1.0 op_sel_hi:[1,0]
	s_add_i32 s5, s5, s26
	v_div_scale_f32 v41, s[10:11], v47, v47, v125
	v_rcp_f32_e32 v43, v41
	s_movk_i32 s14, 0x2cb0
	s_cmp_eq_u32 s4, 3
	s_cselect_b32 s14, 0x2c00, s14
	s_cmp_lt_i32 s5, s14
	v_fma_f32 v48, -v41, v43, 1.0
	v_fmac_f32_e32 v43, v48, v43
	v_div_scale_f32 v48, vcc, v125, v47, v125
	v_mul_f32_e32 v49, v48, v43
	v_fma_f32 v50, -v41, v49, v48
	v_fmac_f32_e32 v49, v50, v43
	v_fma_f32 v41, -v41, v49, v48
	v_div_fmas_f32 v41, v41, v43, v49
	v_div_fixup_f32 v47, v41, v47, v125
	v_div_scale_f32 v41, s[10:11], v46, v46, v124
	v_rcp_f32_e32 v43, v41
	s_nop 0
	v_fma_f32 v48, -v41, v43, 1.0
	v_fmac_f32_e32 v43, v48, v43
	v_div_scale_f32 v48, vcc, v124, v46, v124
	v_mul_f32_e32 v49, v48, v43
	v_fma_f32 v50, -v41, v49, v48
	v_fmac_f32_e32 v49, v50, v43
	v_fma_f32 v41, -v41, v49, v48
	v_div_fmas_f32 v41, v41, v43, v49
	v_div_fixup_f32 v46, v41, v46, v124
	v_mul_f32_e32 v41, 0xbfb8aa3b, v126
	v_exp_f32_e32 v48, v41
	v_mul_f32_e32 v41, 0xbfb8aa3b, v127
	v_exp_f32_e32 v49, v41
	v_pk_mul_f32 v[46:47], v[120:121], v[46:47]
	v_pk_add_f32 v[48:49], v[48:49], 1.0 op_sel_hi:[1,0]
	s_nop 0
	v_div_scale_f32 v41, s[10:11], v49, v49, v127
	v_rcp_f32_e32 v43, v41
	v_cvt_pk_f16_f32 v46, v46, v47
	v_fma_f32 v47, -v41, v43, 1.0
	v_fmac_f32_e32 v43, v47, v43
	v_div_scale_f32 v47, vcc, v127, v49, v127
	v_mul_f32_e32 v50, v47, v43
	v_fma_f32 v51, -v41, v50, v47
	v_fmac_f32_e32 v50, v51, v43
	v_fma_f32 v41, -v41, v50, v47
	v_div_fmas_f32 v41, v41, v43, v50
	v_div_fixup_f32 v49, v41, v49, v127
	v_div_scale_f32 v41, s[10:11], v48, v48, v126
	v_rcp_f32_e32 v43, v41
	s_nop 0
	v_fma_f32 v47, -v41, v43, 1.0
	v_fmac_f32_e32 v43, v47, v43
	v_div_scale_f32 v47, vcc, v126, v48, v126
	v_mul_f32_e32 v50, v47, v43
	v_fma_f32 v51, -v41, v50, v47
	v_fmac_f32_e32 v50, v51, v43
	v_fma_f32 v41, -v41, v50, v47
	v_div_fmas_f32 v41, v41, v43, v50
	v_div_fixup_f32 v48, v41, v48, v126
	v_ashrrev_i32_e32 v41, 31, v40
	v_pk_mul_f32 v[48:49], v[122:123], v[48:49]
	v_lshlrev_b64 v[40:41], 1, v[40:41]
	v_cvt_pk_f16_f32 v47, v48, v49
	v_lshl_add_u64 v[44:45], v[44:45], 0, v[40:41]
	v_mul_f32_e32 v43, 0xbfb8aa3b, v116
	global_store_dwordx2 v[44:45], v[46:47], off
	v_exp_f32_e32 v46, v43
	v_mul_f32_e32 v43, 0xbfb8aa3b, v117
	v_exp_f32_e32 v47, v43
	s_nop 0
	v_pk_add_f32 v[46:47], v[46:47], 1.0 op_sel_hi:[1,0]
	s_nop 0
	v_div_scale_f32 v43, s[10:11], v47, v47, v117
	v_rcp_f32_e32 v48, v43
	s_nop 0
	v_fma_f32 v49, -v43, v48, 1.0
	v_fmac_f32_e32 v48, v49, v48
	v_div_scale_f32 v49, vcc, v117, v47, v117
	v_mul_f32_e32 v50, v49, v48
	v_fma_f32 v51, -v43, v50, v49
	v_fmac_f32_e32 v50, v51, v48
	v_fma_f32 v43, -v43, v50, v49
	v_div_fmas_f32 v43, v43, v48, v50
	v_div_fixup_f32 v47, v43, v47, v117
	v_div_scale_f32 v43, s[10:11], v46, v46, v116
	v_rcp_f32_e32 v48, v43
	s_nop 0
	v_fma_f32 v49, -v43, v48, 1.0
	v_fmac_f32_e32 v48, v49, v48
	v_div_scale_f32 v49, vcc, v116, v46, v116
	v_mul_f32_e32 v50, v49, v48
	v_fma_f32 v51, -v43, v50, v49
	v_fmac_f32_e32 v50, v51, v48
	v_fma_f32 v43, -v43, v50, v49
	v_div_fmas_f32 v43, v43, v48, v50
	v_div_fixup_f32 v46, v43, v46, v116
	v_mul_f32_e32 v43, 0xbfb8aa3b, v118
	v_exp_f32_e32 v48, v43
	v_mul_f32_e32 v43, 0xbfb8aa3b, v119
	v_exp_f32_e32 v49, v43
; __device__ __forceinline__ float siluf_(float x) { return x / (1.0f + __expf(-x)); }
; __device__ __forceinline__ void phase_g4(const Params& p, f16* smem) {
;     ...
;     for (int i = 0; i < 4; ++i) {
;       int m = m0 + wm * 64 + i * 16 + (lane & 15);
; #pragma unroll
;       for (int jj = 0; jj < 2; ++jj) {
;         int u = nt * 64 + wn * 32 + jj * 16 + 4 * (lane >> 4);
;         f16x4 o;
; #pragma unroll
;         for (int r = 0; r < 4; ++r) o[r] = (f16)(siluf_(acc[i][jj][r]) * acc[i][jj + 2][r]);
;         *(f16x4*)(hid + (size_t)m * FF + u) = o;
;       }
;     }
	v_pk_mul_f32 v[46:47], v[112:113], v[46:47]
	v_pk_add_f32 v[48:49], v[48:49], 1.0 op_sel_hi:[1,0]
	s_nop 0
	v_div_scale_f32 v43, s[10:11], v49, v49, v119
	v_cvt_pk_f16_f32 v46, v46, v47
	v_rcp_f32_e32 v47, v43
	s_nop 0
	v_fma_f32 v50, -v43, v47, 1.0
	v_fmac_f32_e32 v47, v50, v47
	v_div_scale_f32 v50, vcc, v119, v49, v119
	v_mul_f32_e32 v51, v50, v47
	v_fma_f32 v52, -v43, v51, v50
	v_fmac_f32_e32 v51, v52, v47
	v_fma_f32 v43, -v43, v51, v50
	v_div_fmas_f32 v43, v43, v47, v51
	v_div_fixup_f32 v49, v43, v49, v119
	v_div_scale_f32 v43, s[10:11], v48, v48, v118
	v_rcp_f32_e32 v47, v43
	s_nop 0
	v_fma_f32 v50, -v43, v47, 1.0
	v_fmac_f32_e32 v47, v50, v47
	v_div_scale_f32 v50, vcc, v118, v48, v118
	v_mul_f32_e32 v51, v50, v47
	v_fma_f32 v52, -v43, v51, v50
	v_fmac_f32_e32 v51, v52, v47
	v_fma_f32 v43, -v43, v51, v50
	v_div_fmas_f32 v43, v43, v47, v51
	v_div_fixup_f32 v48, v43, v48, v118
	v_pk_mul_f32 v[48:49], v[114:115], v[48:49]
	v_or_b32_e32 v43, 16, v42
	v_cvt_pk_f16_f32 v47, v48, v49
	global_store_dwordx2 v[44:45], v[46:47], off offset:32
	v_mad_i64_i32 v[44:45], s[10:11], v43, s96, v[132:133]
	v_mul_f32_e32 v43, 0xbfb8aa3b, v108
	v_exp_f32_e32 v46, v43
	v_mul_f32_e32 v43, 0xbfb8aa3b, v109
	v_exp_f32_e32 v47, v43
	v_lshl_add_u64 v[44:45], v[44:45], 0, v[40:41]
	v_pk_add_f32 v[46:47], v[46:47], 1.0 op_sel_hi:[1,0]
	s_nop 0
	v_div_scale_f32 v43, s[10:11], v47, v47, v109
	v_rcp_f32_e32 v48, v43
	s_nop 0
	v_fma_f32 v49, -v43, v48, 1.0
	v_fmac_f32_e32 v48, v49, v48
	v_div_scale_f32 v49, vcc, v109, v47, v109
	v_mul_f32_e32 v50, v49, v48
	v_fma_f32 v51, -v43, v50, v49
	v_fmac_f32_e32 v50, v51, v48
	v_fma_f32 v43, -v43, v50, v49
	v_div_fmas_f32 v43, v43, v48, v50
	v_div_fixup_f32 v47, v43, v47, v109
	v_div_scale_f32 v43, s[10:11], v46, v46, v108
	v_rcp_f32_e32 v48, v43
	s_nop 0
	v_fma_f32 v49, -v43, v48, 1.0
	v_fmac_f32_e32 v48, v49, v48
	v_div_scale_f32 v49, vcc, v108, v46, v108
	v_mul_f32_e32 v50, v49, v48
	v_fma_f32 v51, -v43, v50, v49
	v_fmac_f32_e32 v50, v51, v48
	v_fma_f32 v43, -v43, v50, v49
	v_div_fmas_f32 v43, v43, v48, v50
	v_div_fixup_f32 v46, v43, v46, v108
	v_mul_f32_e32 v43, 0xbfb8aa3b, v110
	v_exp_f32_e32 v48, v43
	v_mul_f32_e32 v43, 0xbfb8aa3b, v111
	v_exp_f32_e32 v49, v43
	v_pk_mul_f32 v[46:47], v[104:105], v[46:47]
	v_pk_add_f32 v[48:49], v[48:49], 1.0 op_sel_hi:[1,0]
	s_nop 0
	v_div_scale_f32 v43, s[10:11], v49, v49, v111
	v_cvt_pk_f16_f32 v46, v46, v47
	v_rcp_f32_e32 v47, v43
	s_nop 0
	v_fma_f32 v50, -v43, v47, 1.0
	v_fmac_f32_e32 v47, v50, v47
	v_div_scale_f32 v50, vcc, v111, v49, v111
	v_mul_f32_e32 v51, v50, v47
	v_fma_f32 v52, -v43, v51, v50
	v_fmac_f32_e32 v51, v52, v47
	v_fma_f32 v43, -v43, v51, v50
	v_div_fmas_f32 v43, v43, v47, v51
	v_div_fixup_f32 v49, v43, v49, v111
	v_div_scale_f32 v43, s[10:11], v48, v48, v110
	v_rcp_f32_e32 v47, v43
	s_nop 0
	v_fma_f32 v50, -v43, v47, 1.0
	v_fmac_f32_e32 v47, v50, v47
	v_div_scale_f32 v50, vcc, v110, v48, v110
	v_mul_f32_e32 v51, v50, v47
	v_fma_f32 v52, -v43, v51, v50
	v_fmac_f32_e32 v51, v52, v47
	v_fma_f32 v43, -v43, v51, v50
	v_div_fmas_f32 v43, v43, v47, v51
	v_div_fixup_f32 v48, v43, v48, v110
	v_pk_mul_f32 v[48:49], v[106:107], v[48:49]
	v_mul_f32_e32 v43, 0xbfb8aa3b, v36
	v_cvt_pk_f16_f32 v47, v48, v49
	global_store_dwordx2 v[44:45], v[46:47], off
	v_exp_f32_e32 v46, v43
	v_mul_f32_e32 v43, 0xbfb8aa3b, v37
	v_exp_f32_e32 v47, v43
	s_nop 0
	v_pk_add_f32 v[46:47], v[46:47], 1.0 op_sel_hi:[1,0]
	s_nop 0
	v_div_scale_f32 v43, s[10:11], v47, v47, v37
	v_rcp_f32_e32 v48, v43
	s_nop 0
	v_fma_f32 v49, -v43, v48, 1.0
	v_fmac_f32_e32 v48, v49, v48
	v_div_scale_f32 v49, vcc, v37, v47, v37
	v_mul_f32_e32 v50, v49, v48
	v_fma_f32 v51, -v43, v50, v49
	v_fmac_f32_e32 v50, v51, v48
	v_fma_f32 v43, -v43, v50, v49
	v_div_fmas_f32 v43, v43, v48, v50
	v_div_fixup_f32 v37, v43, v47, v37
	v_div_scale_f32 v43, s[10:11], v46, v46, v36
	v_rcp_f32_e32 v47, v43
	s_nop 0
	v_fma_f32 v48, -v43, v47, 1.0
	v_fmac_f32_e32 v47, v48, v47
	v_div_scale_f32 v48, vcc, v36, v46, v36
	v_mul_f32_e32 v49, v48, v47
	v_fma_f32 v50, -v43, v49, v48
	v_fmac_f32_e32 v49, v50, v47
	v_fma_f32 v43, -v43, v49, v48
	v_div_fmas_f32 v43, v43, v47, v49
	v_div_fixup_f32 v36, v43, v46, v36
	v_pk_mul_f32 v[32:33], v[32:33], v[36:37]
	s_nop 0
	v_cvt_pk_f16_f32 v32, v32, v33
	v_mul_f32_e32 v33, 0xbfb8aa3b, v38
	v_exp_f32_e32 v36, v33
	v_mul_f32_e32 v33, 0xbfb8aa3b, v39
	v_exp_f32_e32 v37, v33
	s_nop 0
	v_pk_add_f32 v[36:37], v[36:37], 1.0 op_sel_hi:[1,0]
	s_nop 0
	v_div_scale_f32 v33, s[10:11], v37, v37, v39
	v_rcp_f32_e32 v43, v33
	s_nop 0
	v_fma_f32 v46, -v33, v43, 1.0
	v_fmac_f32_e32 v43, v46, v43
	v_div_scale_f32 v46, vcc, v39, v37, v39
	v_mul_f32_e32 v47, v46, v43
	v_fma_f32 v48, -v33, v47, v46
	v_fmac_f32_e32 v47, v48, v43
	v_fma_f32 v33, -v33, v47, v46
	v_div_fmas_f32 v33, v33, v43, v47
	v_div_fixup_f32 v37, v33, v37, v39
	v_div_scale_f32 v33, s[10:11], v36, v36, v38
	v_rcp_f32_e32 v39, v33
	s_nop 0
	v_fma_f32 v43, -v33, v39, 1.0
	v_fmac_f32_e32 v39, v43, v39
	v_div_scale_f32 v43, vcc, v38, v36, v38
	v_mul_f32_e32 v46, v43, v39
	v_fma_f32 v47, -v33, v46, v43
	v_fmac_f32_e32 v46, v47, v39
	v_fma_f32 v33, -v33, v46, v43
	v_div_fmas_f32 v33, v33, v39, v46
	v_div_fixup_f32 v36, v33, v36, v38
	v_pk_mul_f32 v[34:35], v[34:35], v[36:37]
	s_nop 0
	v_cvt_pk_f16_f32 v33, v34, v35
	v_mul_f32_e32 v34, 0xbfb8aa3b, v28
	v_mul_f32_e32 v35, 0xbfb8aa3b, v29
	v_exp_f32_e32 v34, v34
	v_exp_f32_e32 v35, v35
	global_store_dwordx2 v[44:45], v[32:33], off offset:32
	v_or_b32_e32 v32, 32, v42
	v_mad_i64_i32 v[32:33], s[10:11], v32, s96, v[132:133]
	v_pk_add_f32 v[34:35], v[34:35], 1.0 op_sel_hi:[1,0]
	s_nop 0
	v_div_scale_f32 v36, s[10:11], v35, v35, v29
; __device__ __forceinline__ float siluf_(float x) { return x / (1.0f + __expf(-x)); }
; __device__ __forceinline__ void phase_g4(const Params& p, f16* smem) {
;     ...
;     for (int i = 0; i < 4; ++i) {
;       int m = m0 + wm * 64 + i * 16 + (lane & 15);
; #pragma unroll
;       for (int jj = 0; jj < 2; ++jj) {
;         int u = nt * 64 + wn * 32 + jj * 16 + 4 * (lane >> 4);
;         f16x4 o;
; #pragma unroll
;         for (int r = 0; r < 4; ++r) o[r] = (f16)(siluf_(acc[i][jj][r]) * acc[i][jj + 2][r]);
;         *(f16x4*)(hid + (size_t)m * FF + u) = o;
;       }
;     }
	v_rcp_f32_e32 v37, v36
	s_nop 0
	v_fma_f32 v38, -v36, v37, 1.0
	v_fmac_f32_e32 v37, v38, v37
	v_div_scale_f32 v38, vcc, v29, v35, v29
	v_mul_f32_e32 v39, v38, v37
	v_fma_f32 v43, -v36, v39, v38
	v_fmac_f32_e32 v39, v43, v37
	v_fma_f32 v36, -v36, v39, v38
	v_div_fmas_f32 v36, v36, v37, v39
	v_div_fixup_f32 v29, v36, v35, v29
	v_div_scale_f32 v35, s[10:11], v34, v34, v28
	v_rcp_f32_e32 v36, v35
	s_nop 0
	v_fma_f32 v37, -v35, v36, 1.0
	v_fmac_f32_e32 v36, v37, v36
	v_div_scale_f32 v37, vcc, v28, v34, v28
	v_mul_f32_e32 v38, v37, v36
	v_fma_f32 v39, -v35, v38, v37
	v_fmac_f32_e32 v38, v39, v36
	v_fma_f32 v35, -v35, v38, v37
	v_div_fmas_f32 v35, v35, v36, v38
	v_div_fixup_f32 v28, v35, v34, v28
	v_pk_mul_f32 v[24:25], v[24:25], v[28:29]
	s_nop 0
	v_cvt_pk_f16_f32 v24, v24, v25
	v_mul_f32_e32 v25, 0xbfb8aa3b, v30
	v_exp_f32_e32 v28, v25
	v_mul_f32_e32 v25, 0xbfb8aa3b, v31
	v_exp_f32_e32 v29, v25
	s_nop 0
	v_pk_add_f32 v[28:29], v[28:29], 1.0 op_sel_hi:[1,0]
	s_nop 0
	v_div_scale_f32 v25, s[10:11], v29, v29, v31
	v_rcp_f32_e32 v34, v25
	s_nop 0
	v_fma_f32 v35, -v25, v34, 1.0
	v_fmac_f32_e32 v34, v35, v34
	v_div_scale_f32 v35, vcc, v31, v29, v31
	v_mul_f32_e32 v36, v35, v34
	v_fma_f32 v37, -v25, v36, v35
	v_fmac_f32_e32 v36, v37, v34
	v_fma_f32 v25, -v25, v36, v35
	v_div_fmas_f32 v25, v25, v34, v36
	v_div_fixup_f32 v29, v25, v29, v31
	v_div_scale_f32 v25, s[10:11], v28, v28, v30
	v_rcp_f32_e32 v31, v25
	s_nop 0
	v_fma_f32 v34, -v25, v31, 1.0
	v_fmac_f32_e32 v31, v34, v31
	v_div_scale_f32 v34, vcc, v30, v28, v30
	v_mul_f32_e32 v35, v34, v31
	v_fma_f32 v36, -v25, v35, v34
	v_fmac_f32_e32 v35, v36, v31
	v_fma_f32 v25, -v25, v35, v34
	v_div_fmas_f32 v25, v25, v31, v35
	v_div_fixup_f32 v28, v25, v28, v30
	v_pk_mul_f32 v[26:27], v[26:27], v[28:29]
	s_nop 0
	v_cvt_pk_f16_f32 v25, v26, v27
	v_lshl_add_u64 v[26:27], v[32:33], 0, v[40:41]
	global_store_dwordx2 v[26:27], v[24:25], off
	v_mul_f32_e32 v24, 0xbfb8aa3b, v20
	v_mul_f32_e32 v25, 0xbfb8aa3b, v21
	v_exp_f32_e32 v24, v24
	v_exp_f32_e32 v25, v25
	s_nop 0
	v_pk_add_f32 v[24:25], v[24:25], 1.0 op_sel_hi:[1,0]
	s_nop 0
	v_div_scale_f32 v28, s[10:11], v25, v25, v21
	v_rcp_f32_e32 v29, v28
	s_nop 0
	v_fma_f32 v30, -v28, v29, 1.0
	v_fmac_f32_e32 v29, v30, v29
	v_div_scale_f32 v30, vcc, v21, v25, v21
	v_mul_f32_e32 v31, v30, v29
	v_fma_f32 v32, -v28, v31, v30
	v_fmac_f32_e32 v31, v32, v29
	v_fma_f32 v28, -v28, v31, v30
	v_div_fmas_f32 v28, v28, v29, v31
	v_div_fixup_f32 v21, v28, v25, v21
	v_div_scale_f32 v25, s[10:11], v24, v24, v20
	v_rcp_f32_e32 v28, v25
	s_nop 0
	v_fma_f32 v29, -v25, v28, 1.0
	v_fmac_f32_e32 v28, v29, v28
	v_div_scale_f32 v29, vcc, v20, v24, v20
	v_mul_f32_e32 v30, v29, v28
	v_fma_f32 v31, -v25, v30, v29
	v_fmac_f32_e32 v30, v31, v28
	v_fma_f32 v25, -v25, v30, v29
	v_div_fmas_f32 v25, v25, v28, v30
	v_div_fixup_f32 v20, v25, v24, v20
	v_pk_mul_f32 v[16:17], v[16:17], v[20:21]
	s_nop 0
	v_cvt_pk_f16_f32 v16, v16, v17
	v_mul_f32_e32 v17, 0xbfb8aa3b, v22
	v_exp_f32_e32 v20, v17
	v_mul_f32_e32 v17, 0xbfb8aa3b, v23
	v_exp_f32_e32 v21, v17
	s_nop 0
	v_pk_add_f32 v[20:21], v[20:21], 1.0 op_sel_hi:[1,0]
	s_nop 0
	v_div_scale_f32 v17, s[10:11], v21, v21, v23
	v_rcp_f32_e32 v24, v17
	s_nop 0
	v_fma_f32 v25, -v17, v24, 1.0
	v_fmac_f32_e32 v24, v25, v24
	v_div_scale_f32 v25, vcc, v23, v21, v23
	v_mul_f32_e32 v28, v25, v24
	v_fma_f32 v29, -v17, v28, v25
	v_fmac_f32_e32 v28, v29, v24
	v_fma_f32 v17, -v17, v28, v25
	v_div_fmas_f32 v17, v17, v24, v28
	v_div_fixup_f32 v21, v17, v21, v23
	v_div_scale_f32 v17, s[10:11], v20, v20, v22
	v_rcp_f32_e32 v23, v17
	s_nop 0
	v_fma_f32 v24, -v17, v23, 1.0
	v_fmac_f32_e32 v23, v24, v23
	v_div_scale_f32 v24, vcc, v22, v20, v22
	v_mul_f32_e32 v25, v24, v23
	v_fma_f32 v28, -v17, v25, v24
	v_fmac_f32_e32 v25, v28, v23
	v_fma_f32 v17, -v17, v25, v24
	v_div_fmas_f32 v17, v17, v23, v25
	v_div_fixup_f32 v20, v17, v20, v22
	v_pk_mul_f32 v[18:19], v[18:19], v[20:21]
	s_nop 0
	v_cvt_pk_f16_f32 v17, v18, v19
	v_mul_f32_e32 v18, 0xbfb8aa3b, v12
	v_mul_f32_e32 v19, 0xbfb8aa3b, v13
	v_exp_f32_e32 v18, v18
	v_exp_f32_e32 v19, v19
; __device__ __forceinline__ float siluf_(float x) { return x / (1.0f + __expf(-x)); }
; __device__ __forceinline__ void phase_g4(const Params& p, f16* smem) {
;     ...
;     for (int i = 0; i < 4; ++i) {
;       int m = m0 + wm * 64 + i * 16 + (lane & 15);
; #pragma unroll
;       for (int jj = 0; jj < 2; ++jj) {
;         int u = nt * 64 + wn * 32 + jj * 16 + 4 * (lane >> 4);
;         f16x4 o;
; #pragma unroll
;         for (int r = 0; r < 4; ++r) o[r] = (f16)(siluf_(acc[i][jj][r]) * acc[i][jj + 2][r]);
;         *(f16x4*)(hid + (size_t)m * FF + u) = o;
;       }
;     }
	global_store_dwordx2 v[26:27], v[16:17], off offset:32
	v_or_b32_e32 v16, 48, v42
	v_mad_i64_i32 v[16:17], s[10:11], v16, s96, v[132:133]
	v_pk_add_f32 v[18:19], v[18:19], 1.0 op_sel_hi:[1,0]
	s_nop 0
	v_div_scale_f32 v20, s[10:11], v19, v19, v13
	v_rcp_f32_e32 v21, v20
	s_nop 0
	v_fma_f32 v22, -v20, v21, 1.0
	v_fmac_f32_e32 v21, v22, v21
	v_div_scale_f32 v22, vcc, v13, v19, v13
	v_mul_f32_e32 v23, v22, v21
	v_fma_f32 v24, -v20, v23, v22
	v_fmac_f32_e32 v23, v24, v21
	v_fma_f32 v20, -v20, v23, v22
	v_div_fmas_f32 v20, v20, v21, v23
	v_div_fixup_f32 v13, v20, v19, v13
	v_div_scale_f32 v19, s[10:11], v18, v18, v12
	v_rcp_f32_e32 v20, v19
	s_nop 0
	v_fma_f32 v21, -v19, v20, 1.0
	v_fmac_f32_e32 v20, v21, v20
	v_div_scale_f32 v21, vcc, v12, v18, v12
	v_mul_f32_e32 v22, v21, v20
	v_fma_f32 v23, -v19, v22, v21
	v_fmac_f32_e32 v22, v23, v20
	v_fma_f32 v19, -v19, v22, v21
	v_div_fmas_f32 v19, v19, v20, v22
	v_div_fixup_f32 v12, v19, v18, v12
	v_pk_mul_f32 v[8:9], v[8:9], v[12:13]
	s_nop 0
	v_cvt_pk_f16_f32 v8, v8, v9
	v_mul_f32_e32 v9, 0xbfb8aa3b, v14
	v_exp_f32_e32 v12, v9
	v_mul_f32_e32 v9, 0xbfb8aa3b, v15
	v_exp_f32_e32 v13, v9
	s_nop 0
	v_pk_add_f32 v[12:13], v[12:13], 1.0 op_sel_hi:[1,0]
	s_nop 0
	v_div_scale_f32 v9, s[10:11], v13, v13, v15
	v_rcp_f32_e32 v18, v9
	s_nop 0
	v_fma_f32 v19, -v9, v18, 1.0
	v_fmac_f32_e32 v18, v19, v18
	v_div_scale_f32 v19, vcc, v15, v13, v15
	v_mul_f32_e32 v20, v19, v18
	v_fma_f32 v21, -v9, v20, v19
	v_fmac_f32_e32 v20, v21, v18
	v_fma_f32 v9, -v9, v20, v19
	v_div_fmas_f32 v9, v9, v18, v20
	v_div_fixup_f32 v13, v9, v13, v15
	v_div_scale_f32 v9, s[10:11], v12, v12, v14
	v_rcp_f32_e32 v15, v9
	s_nop 0
	v_fma_f32 v18, -v9, v15, 1.0
	v_fmac_f32_e32 v15, v18, v15
	v_div_scale_f32 v18, vcc, v14, v12, v14
	v_mul_f32_e32 v19, v18, v15
	v_fma_f32 v20, -v9, v19, v18
	v_fmac_f32_e32 v19, v20, v15
	v_fma_f32 v9, -v9, v19, v18
	v_div_fmas_f32 v9, v9, v15, v19
	v_div_fixup_f32 v12, v9, v12, v14
	v_pk_mul_f32 v[10:11], v[10:11], v[12:13]
	s_nop 0
	v_cvt_pk_f16_f32 v9, v10, v11
	v_lshl_add_u64 v[10:11], v[16:17], 0, v[40:41]
	global_store_dwordx2 v[10:11], v[8:9], off
	v_mul_f32_e32 v8, 0xbfb8aa3b, v4
	v_mul_f32_e32 v9, 0xbfb8aa3b, v5
	v_exp_f32_e32 v8, v8
	v_exp_f32_e32 v9, v9
	s_nop 0
	v_pk_add_f32 v[8:9], v[8:9], 1.0 op_sel_hi:[1,0]
	s_nop 0
	v_div_scale_f32 v12, s[10:11], v9, v9, v5
	v_rcp_f32_e32 v13, v12
	s_nop 0
	v_fma_f32 v14, -v12, v13, 1.0
	v_fmac_f32_e32 v13, v14, v13
	v_div_scale_f32 v14, vcc, v5, v9, v5
	v_mul_f32_e32 v15, v14, v13
	v_fma_f32 v16, -v12, v15, v14
	v_fmac_f32_e32 v15, v16, v13
	v_fma_f32 v12, -v12, v15, v14
	v_div_fmas_f32 v12, v12, v13, v15
	v_div_fixup_f32 v5, v12, v9, v5
	v_div_scale_f32 v9, s[10:11], v8, v8, v4
	v_rcp_f32_e32 v12, v9
	s_nop 0
	v_fma_f32 v13, -v9, v12, 1.0
	v_fmac_f32_e32 v12, v13, v12
	v_div_scale_f32 v13, vcc, v4, v8, v4
	v_mul_f32_e32 v14, v13, v12
	v_fma_f32 v15, -v9, v14, v13
	v_fmac_f32_e32 v14, v15, v12
	v_fma_f32 v9, -v9, v14, v13
	v_div_fmas_f32 v9, v9, v12, v14
	v_div_fixup_f32 v4, v9, v8, v4
	v_pk_mul_f32 v[0:1], v[0:1], v[4:5]
	s_nop 0
	v_cvt_pk_f16_f32 v0, v0, v1
	v_mul_f32_e32 v1, 0xbfb8aa3b, v6
	v_exp_f32_e32 v4, v1
	v_mul_f32_e32 v1, 0xbfb8aa3b, v7
	v_exp_f32_e32 v5, v1
	s_nop 0
	v_pk_add_f32 v[4:5], v[4:5], 1.0 op_sel_hi:[1,0]
	s_nop 0
	v_div_scale_f32 v1, s[10:11], v5, v5, v7
	v_rcp_f32_e32 v8, v1
	s_nop 0
	v_fma_f32 v9, -v1, v8, 1.0
	v_fmac_f32_e32 v8, v9, v8
	v_div_scale_f32 v9, vcc, v7, v5, v7
	v_mul_f32_e32 v12, v9, v8
	v_fma_f32 v13, -v1, v12, v9
	v_fmac_f32_e32 v12, v13, v8
	v_fma_f32 v1, -v1, v12, v9
	v_div_fmas_f32 v1, v1, v8, v12
	v_div_fixup_f32 v5, v1, v5, v7
	v_div_scale_f32 v1, s[10:11], v4, v4, v6
	v_rcp_f32_e32 v7, v1
	s_nop 0
	v_fma_f32 v8, -v1, v7, 1.0
	v_fmac_f32_e32 v7, v8, v7
	v_div_scale_f32 v8, vcc, v6, v4, v6
	v_mul_f32_e32 v9, v8, v7
	v_fma_f32 v12, -v1, v9, v8
	v_fmac_f32_e32 v9, v12, v7
	v_fma_f32 v1, -v1, v9, v8
	v_div_fmas_f32 v1, v1, v7, v9
	v_div_fixup_f32 v4, v1, v4, v6
	v_pk_mul_f32 v[2:3], v[2:3], v[4:5]
	s_nop 0
	v_cvt_pk_f16_f32 v1, v2, v3
	global_store_dwordx2 v[10:11], v[0:1], off offset:32
	s_cbranch_scc1 .LBB0_1397

; template <int NJ>
; __device__ __forceinline__ void gemm_tile(const f16* __restrict__ A, int lda, const f16* __restrict__ Bt, int ldb,
;                                           int K, f32x4 (&acc)[4][NJ], f16* sA, f16* sB, const int tid) {
;     ...
;   G_LOAD(ra0, rb0, 0)
;   if (K > 64) G_LOAD(ra1, rb1, 64)
;   __syncthreads();
;   G_STORE(ra0, rb0, 0)
;   if (K > 128) G_LOAD(ra0, rb0, 128)
;   __syncthreads();
; __device__ __forceinline__ void phase_gres(const Params& p, int l, const f16* A, int lda, const f16* W, int K, int gate_idx,
;                            bool first_in, f16* smem) {
;     ...
;   const int full = (MT * NT / (int)gridDim.x) * (int)gridDim.x;
;   for (int t = blockIdx.x; t < full; t += gridDim.x)
;     gres_tile<4>(p, A, lda, W, K, mod, first_in, sA, sB, (t / NT) * 128, (t % NT) * 128);
.LBB0_1456:
	s_mov_b32 s10, s5
	s_cmpk_lg_u32 s26, 0x200
	s_cbranch_scc1 .Lxm_g5
	s_cmpk_ge_u32 s5, 0x800
	s_cbranch_scc1 .Lxm_g5
	s_and_b32 s10, s5, 7
	s_lshl_b32 s10, s10, 2
	s_lshr_b32 s11, s5, 9
	s_add_i32 s10, s10, s11
	s_lshl_b32 s10, s10, 6
	s_bfe_u32 s11, s5, 0x60003
	s_or_b32 s10, s10, s11
.Lxm_g5:
	s_ashr_i32 s6, s10, 31
	s_lshr_b32 s6, s6, 29
	s_add_i32 s7, s10, s6
	s_lshl_b32 s6, s7, 4
	s_and_b32 s6, s6, 0xffffff80
	v_mad_i64_i32 v[146:147], s[12:13], s6, v191, v[142:143]
	v_add_co_u32_e32 v2, vcc, 0x2c000, v146
	s_and_b32 s7, s7, -8
	s_nop 0
	v_addc_co_u32_e32 v3, vcc, 0, v147, vcc
	s_sub_i32 s7, s10, s7
	v_add_co_u32_e32 v4, vcc, s97, v146
	s_mul_i32 s10, s7, 0x58000
	s_nop 0
	v_addc_co_u32_e32 v5, vcc, 0, v147, vcc
	s_ashr_i32 s11, s10, 31
	v_add_co_u32_e32 v6, vcc, 0x84000, v146
	v_lshl_add_u64 v[148:149], s[10:11], 1, v[144:145]
	s_nop 0
	v_addc_co_u32_e32 v7, vcc, 0, v147, vcc
	v_add_co_u32_e32 v8, vcc, s81, v148
	global_load_dwordx4 v[82:85], v[146:147], off
	s_nop 0
	v_addc_co_u32_e32 v9, vcc, 0, v149, vcc
	v_add_co_u32_e32 v10, vcc, s97, v148
	global_load_dwordx4 v[86:89], v[2:3], off
	s_nop 0
	v_addc_co_u32_e32 v11, vcc, 0, v149, vcc
	v_add_co_u32_e32 v12, vcc, s27, v148
	global_load_dwordx4 v[90:93], v[4:5], off
	s_nop 0
	v_addc_co_u32_e32 v13, vcc, 0, v149, vcc
	global_load_dwordx4 v[94:97], v[6:7], off
	global_load_dwordx4 v[98:101], v[148:149], off
	global_load_dwordx4 v[102:105], v[8:9], off
	global_load_dwordx4 v[106:109], v[10:11], off
	global_load_dwordx4 v[110:113], v[12:13], off
	global_load_dwordx4 v[18:21], v[146:147], off offset:128
	global_load_dwordx4 v[26:29], v[2:3], off offset:128
	global_load_dwordx4 v[22:25], v[148:149], off offset:128
	global_load_dwordx4 v[30:33], v[4:5], off offset:128
	global_load_dwordx4 v[34:37], v[6:7], off offset:128
	global_load_dwordx4 v[38:41], v[8:9], off offset:128
	global_load_dwordx4 v[46:49], v[10:11], off offset:128
	global_load_dwordx4 v[50:53], v[12:13], off offset:128
	s_barrier
	global_load_dwordx4 v[58:61], v[2:3], off offset:256
	global_load_dwordx4 v[62:65], v[4:5], off offset:256
	global_load_dwordx4 v[42:45], v[146:147], off offset:256
	global_load_dwordx4 v[54:57], v[148:149], off offset:256
	global_load_dwordx4 v[66:69], v[6:7], off offset:256
	global_load_dwordx4 v[70:73], v[8:9], off offset:256
	global_load_dwordx4 v[74:77], v[10:11], off offset:256
	global_load_dwordx4 v[78:81], v[12:13], off offset:256
	v_mov_b32_e32 v2, 0
	s_mov_b32 s10, 0
	v_mov_b32_e32 v3, v2
	v_mov_b32_e32 v4, v2
	v_mov_b32_e32 v5, v2
	v_mov_b32_e32 v6, v2
	v_mov_b32_e32 v7, v2
	v_mov_b32_e32 v8, v2
	v_mov_b32_e32 v9, v2
	v_mov_b32_e32 v10, v2
	v_mov_b32_e32 v11, v2
	v_mov_b32_e32 v12, v2
	v_mov_b32_e32 v13, v2
	v_mov_b32_e32 v14, v2
	v_mov_b32_e32 v15, v2
	v_mov_b32_e32 v16, v2
	v_mov_b32_e32 v17, v2
	v_mov_b32_e32 v114, v2
	v_mov_b32_e32 v115, v2
	v_mov_b32_e32 v116, v2
	v_mov_b32_e32 v117, v2
	v_mov_b32_e32 v118, v2
	v_mov_b32_e32 v119, v2
	v_mov_b32_e32 v120, v2
	v_mov_b32_e32 v121, v2
	v_mov_b32_e32 v122, v2
	v_mov_b32_e32 v123, v2
	v_mov_b32_e32 v124, v2
	v_mov_b32_e32 v125, v2
	v_mov_b32_e32 v126, v2
	v_mov_b32_e32 v127, v2
	v_mov_b32_e32 v128, v2
	v_mov_b32_e32 v129, v2
	s_waitcnt vmcnt(23)
	ds_write_b128 v161, v[82:85]
	s_waitcnt vmcnt(22)
	ds_write_b128 v161, v[86:89] offset:4096
	s_waitcnt vmcnt(19)
	ds_write_b128 v161, v[98:101] offset:16384
	ds_write_b128 v161, v[90:93] offset:8192
	ds_write_b128 v161, v[94:97] offset:12288
	s_waitcnt vmcnt(18)
	ds_write_b128 v161, v[102:105] offset:20480
	s_waitcnt vmcnt(17)
	ds_write_b128 v161, v[106:109] offset:24576
	s_waitcnt vmcnt(16)
	ds_write_b128 v161, v[110:113] offset:28672
	s_waitcnt lgkmcnt(0)
	s_barrier
	v_mov_b32_e32 v82, v2
	v_mov_b32_e32 v83, v2
	v_mov_b32_e32 v84, v2
	v_mov_b32_e32 v85, v2
	v_mov_b32_e32 v86, v2
	v_mov_b32_e32 v87, v2
	v_mov_b32_e32 v88, v2
	v_mov_b32_e32 v89, v2
	v_mov_b32_e32 v90, v2
	v_mov_b32_e32 v91, v2
	v_mov_b32_e32 v92, v2
	v_mov_b32_e32 v93, v2
	v_mov_b32_e32 v94, v2
	v_mov_b32_e32 v95, v2
	v_mov_b32_e32 v96, v2
	v_mov_b32_e32 v97, v2
	v_mov_b32_e32 v98, v2
	v_mov_b32_e32 v99, v2
	v_mov_b32_e32 v100, v2
	v_mov_b32_e32 v101, v2
	v_mov_b32_e32 v102, v2
	v_mov_b32_e32 v103, v2
	v_mov_b32_e32 v104, v2
	v_mov_b32_e32 v105, v2
	v_mov_b32_e32 v106, v2
	v_mov_b32_e32 v107, v2
	v_mov_b32_e32 v108, v2
	v_mov_b32_e32 v109, v2
	v_mov_b32_e32 v110, v2
	v_mov_b32_e32 v111, v2
	v_mov_b32_e32 v112, v2
	v_mov_b32_e32 v113, v2
.LBB0_1457:
	ds_read_b128 v[204:207], v163 offset:16384
	ds_read_b128 v[208:211], v163 offset:18432
	ds_read_b128 v[212:215], v163 offset:20480
	ds_read_b128 v[216:219], v163 offset:22528
	s_add_i32 s11, s10, 0xc0
	ds_read_b128 v[192:195], v162
	ds_read_b128 v[196:199], v162 offset:2048
	s_cmpk_lt_u32 s10, 0xa40
	s_cselect_b32 s42, s11, 0xac0
	ds_read_b128 v[200:203], v162 offset:4096
	s_lshl_b64 s[12:13], s[42:43], 1
	v_lshl_add_u64 v[152:153], v[146:147], 0, s[12:13]
	ds_read_b128 v[130:133], v162 offset:6144
	ds_read_b128 v[244:247], v243 offset:16384
	ds_read_b128 v[248:251], v243 offset:18432
	ds_read_b128 v[252:255], v243 offset:20480
	s_waitcnt lgkmcnt(6)
	v_mfma_f32_16x16x32_f16 v[126:129], v[204:207], v[192:195], v[126:129]
	v_lshl_add_u64 v[150:151], v[148:149], 0, s[12:13]
	s_add_i32 s11, s10, 0x100
	s_cmpk_lt_u32 s10, 0xa00
	v_mfma_f32_16x16x32_f16 v[122:125], v[208:211], v[192:195], v[122:125]
	s_cselect_b32 s42, s11, 0xac0
	s_lshl_b64 s[12:13], s[42:43], 1
	v_lshl_add_u64 v[168:169], v[148:149], 0, s[12:13]
	v_mfma_f32_16x16x32_f16 v[118:121], v[212:215], v[192:195], v[118:121]
	s_add_i32 s11, s10, 0x80
	s_cmpk_lt_u32 s10, 0xa80
	s_mov_b32 s10, s11
	v_mfma_f32_16x16x32_f16 v[114:117], v[216:219], v[192:195], v[114:117]
	ds_read_b128 v[192:195], v243 offset:22528
	s_waitcnt vmcnt(15)
	ds_write_b128 v161, v[18:21] offset:32768
	global_load_dwordx4 v[18:21], v[152:153], off
	s_waitcnt lgkmcnt(7)
	v_mfma_f32_16x16x32_f16 v[110:113], v[204:207], v[196:199], v[110:113]
	v_mfma_f32_16x16x32_f16 v[106:109], v[208:211], v[196:199], v[106:109]
	v_mfma_f32_16x16x32_f16 v[102:105], v[212:215], v[196:199], v[102:105]
	v_mfma_f32_16x16x32_f16 v[98:101], v[216:219], v[196:199], v[98:101]
	ds_read_b128 v[196:199], v242
	s_waitcnt vmcnt(15)
	ds_write_b128 v161, v[26:29] offset:36864
	v_add_co_u32_e32 v26, vcc, s81, v152
	s_nop 1
	v_addc_co_u32_e32 v27, vcc, 0, v153, vcc
	global_load_dwordx4 v[26:29], v[26:27], off
	s_waitcnt lgkmcnt(8)
	v_mfma_f32_16x16x32_f16 v[94:97], v[204:207], v[200:203], v[94:97]
	v_mfma_f32_16x16x32_f16 v[90:93], v[208:211], v[200:203], v[90:93]
	v_mfma_f32_16x16x32_f16 v[86:89], v[212:215], v[200:203], v[86:89]
	v_mfma_f32_16x16x32_f16 v[82:85], v[216:219], v[200:203], v[82:85]
	ds_read_b128 v[200:203], v242 offset:2048
	s_waitcnt vmcnt(14)
	ds_write_b128 v161, v[30:33] offset:40960
	v_add_co_u32_e32 v30, vcc, s97, v152
	s_nop 1
	v_addc_co_u32_e32 v31, vcc, 0, v153, vcc
	global_load_dwordx4 v[30:33], v[30:31], off
	s_waitcnt lgkmcnt(9)
	v_mfma_f32_16x16x32_f16 v[14:17], v[204:207], v[130:133], v[14:17]
	v_mfma_f32_16x16x32_f16 v[10:13], v[208:211], v[130:133], v[10:13]
	v_mfma_f32_16x16x32_f16 v[6:9], v[212:215], v[130:133], v[6:9]
	v_mfma_f32_16x16x32_f16 v[2:5], v[216:219], v[130:133], v[2:5]
	ds_read_b128 v[130:133], v242 offset:4096
	ds_read_b128 v[204:207], v242 offset:6144
	s_waitcnt vmcnt(14)
	ds_write_b128 v161, v[34:37] offset:45056
	v_add_co_u32_e32 v34, vcc, s27, v152
	s_nop 1
	v_addc_co_u32_e32 v35, vcc, 0, v153, vcc
	global_load_dwordx4 v[34:37], v[34:35], off
	s_waitcnt lgkmcnt(6)
	v_mfma_f32_16x16x32_f16 v[126:129], v[244:247], v[196:199], v[126:129]
	v_mfma_f32_16x16x32_f16 v[122:125], v[248:251], v[196:199], v[122:125]
	v_mfma_f32_16x16x32_f16 v[118:121], v[252:255], v[196:199], v[118:121]
	v_mfma_f32_16x16x32_f16 v[114:117], v[192:195], v[196:199], v[114:117]
	ds_write_b128 v161, v[22:25] offset:49152
	global_load_dwordx4 v[22:25], v[150:151], off
	v_lshl_add_u64 v[216:217], v[146:147], 0, s[12:13]
	s_waitcnt lgkmcnt(5)
	v_mfma_f32_16x16x32_f16 v[110:113], v[244:247], v[200:203], v[110:113]
	v_mfma_f32_16x16x32_f16 v[106:109], v[248:251], v[200:203], v[106:109]
	v_mfma_f32_16x16x32_f16 v[102:105], v[252:255], v[200:203], v[102:105]
	v_mfma_f32_16x16x32_f16 v[98:101], v[192:195], v[200:203], v[98:101]
	s_waitcnt vmcnt(15)
	ds_write_b128 v161, v[38:41] offset:53248
	v_add_co_u32_e32 v38, vcc, s81, v150
	s_nop 1
	v_addc_co_u32_e32 v39, vcc, 0, v151, vcc
	global_load_dwordx4 v[38:41], v[38:39], off
	s_waitcnt lgkmcnt(4)
	v_mfma_f32_16x16x32_f16 v[94:97], v[244:247], v[130:133], v[94:97]
	v_mfma_f32_16x16x32_f16 v[90:93], v[248:251], v[130:133], v[90:93]
	v_mfma_f32_16x16x32_f16 v[86:89], v[252:255], v[130:133], v[86:89]
	v_mfma_f32_16x16x32_f16 v[82:85], v[192:195], v[130:133], v[82:85]
	s_waitcnt vmcnt(15)
	ds_write_b128 v161, v[46:49] offset:57344
	v_add_co_u32_e32 v46, vcc, s97, v150
	s_nop 1
	v_addc_co_u32_e32 v47, vcc, 0, v151, vcc
	global_load_dwordx4 v[46:49], v[46:47], off
	s_waitcnt lgkmcnt(4)
	v_mfma_f32_16x16x32_f16 v[14:17], v[244:247], v[204:207], v[14:17]
	v_mfma_f32_16x16x32_f16 v[10:13], v[248:251], v[204:207], v[10:13]
	v_mfma_f32_16x16x32_f16 v[6:9], v[252:255], v[204:207], v[6:9]
	v_mfma_f32_16x16x32_f16 v[2:5], v[192:195], v[204:207], v[2:5]
	s_waitcnt vmcnt(15)
	ds_write_b128 v161, v[50:53] offset:61440
	v_add_co_u32_e32 v50, vcc, s27, v150
	s_nop 1
	v_addc_co_u32_e32 v51, vcc, 0, v151, vcc
	global_load_dwordx4 v[50:53], v[50:51], off
	s_waitcnt lgkmcnt(0)
	s_barrier
; template <int NJ>
; __device__ __forceinline__ void gemm_tile(const f16* __restrict__ A, int lda, const f16* __restrict__ Bt, int ldb,
;                                           int K, f32x4 (&acc)[4][NJ], f16* sA, f16* sB, const int tid) {
;     ...
;   G_LOAD(ra0, rb0, 0)
;   if (K > 64) G_LOAD(ra1, rb1, 64)
;   __syncthreads();
;   G_STORE(ra0, rb0, 0)
;   if (K > 128) G_LOAD(ra0, rb0, 128)
;   __syncthreads();
; #pragma unroll 1
;   for (int k0 = 0; k0 < K; k0 += 128) {
;     {
;       const int kof = (k0 + 192 < K) ? k0 + 192 : K - 64;
;       G_STEP(0, ra1, rb1, true, true, kof)
;     }
;     __syncthreads();
;     if (k0 + 64 >= K) break;
;     {
;       const int kof = (k0 + 256 < K) ? k0 + 256 : K - 64;
;       G_STEP(1, ra0, rb0, true, true, kof)
;     }
;     __syncthreads();
	ds_read_b128 v[200:203], v163 offset:49152
	ds_read_b128 v[204:207], v163 offset:51200
	ds_read_b128 v[208:211], v163 offset:53248
	ds_read_b128 v[212:215], v163 offset:55296
	ds_read_b128 v[130:133], v162 offset:32768
	ds_read_b128 v[150:153], v162 offset:34816
	ds_read_b128 v[192:195], v162 offset:36864
	ds_read_b128 v[196:199], v162 offset:38912
	ds_read_b128 v[244:247], v243 offset:49152
	ds_read_b128 v[248:251], v243 offset:51200
	ds_read_b128 v[252:255], v243 offset:53248
	s_waitcnt lgkmcnt(6)
	v_mfma_f32_16x16x32_f16 v[126:129], v[200:203], v[130:133], v[126:129]
	v_mfma_f32_16x16x32_f16 v[122:125], v[204:207], v[130:133], v[122:125]
	v_mfma_f32_16x16x32_f16 v[118:121], v[208:211], v[130:133], v[118:121]
	v_mfma_f32_16x16x32_f16 v[114:117], v[212:215], v[130:133], v[114:117]
	ds_read_b128 v[130:133], v243 offset:55296
	s_waitcnt vmcnt(13)
	ds_write_b128 v161, v[42:45]
	global_load_dwordx4 v[42:45], v[216:217], off
	s_waitcnt lgkmcnt(7)
	v_mfma_f32_16x16x32_f16 v[110:113], v[200:203], v[150:153], v[110:113]
	v_mfma_f32_16x16x32_f16 v[106:109], v[204:207], v[150:153], v[106:109]
	v_mfma_f32_16x16x32_f16 v[102:105], v[208:211], v[150:153], v[102:105]
	v_mfma_f32_16x16x32_f16 v[98:101], v[212:215], v[150:153], v[98:101]
	ds_read_b128 v[150:153], v242 offset:32768
	ds_write_b128 v161, v[58:61] offset:4096
	v_add_co_u32_e32 v58, vcc, s81, v216
	s_nop 1
	v_addc_co_u32_e32 v59, vcc, 0, v217, vcc
	global_load_dwordx4 v[58:61], v[58:59], off
	s_waitcnt lgkmcnt(8)
	v_mfma_f32_16x16x32_f16 v[94:97], v[200:203], v[192:195], v[94:97]
	v_mfma_f32_16x16x32_f16 v[90:93], v[204:207], v[192:195], v[90:93]
	v_mfma_f32_16x16x32_f16 v[86:89], v[208:211], v[192:195], v[86:89]
	v_mfma_f32_16x16x32_f16 v[82:85], v[212:215], v[192:195], v[82:85]
	ds_read_b128 v[192:195], v242 offset:34816
	ds_write_b128 v161, v[62:65] offset:8192
	v_add_co_u32_e32 v62, vcc, s97, v216
	s_nop 1
	v_addc_co_u32_e32 v63, vcc, 0, v217, vcc
	global_load_dwordx4 v[62:65], v[62:63], off
	s_waitcnt lgkmcnt(9)
	v_mfma_f32_16x16x32_f16 v[14:17], v[200:203], v[196:199], v[14:17]
	v_mfma_f32_16x16x32_f16 v[10:13], v[204:207], v[196:199], v[10:13]
	v_mfma_f32_16x16x32_f16 v[6:9], v[208:211], v[196:199], v[6:9]
	v_mfma_f32_16x16x32_f16 v[2:5], v[212:215], v[196:199], v[2:5]
	ds_read_b128 v[196:199], v242 offset:36864
	ds_read_b128 v[200:203], v242 offset:38912
	s_waitcnt vmcnt(14)
	ds_write_b128 v161, v[66:69] offset:12288
	v_add_co_u32_e32 v66, vcc, s27, v216
	s_nop 1
	v_addc_co_u32_e32 v67, vcc, 0, v217, vcc
	global_load_dwordx4 v[66:69], v[66:67], off
	s_waitcnt lgkmcnt(6)
	v_mfma_f32_16x16x32_f16 v[126:129], v[244:247], v[150:153], v[126:129]
	v_mfma_f32_16x16x32_f16 v[122:125], v[248:251], v[150:153], v[122:125]
	v_mfma_f32_16x16x32_f16 v[118:121], v[252:255], v[150:153], v[118:121]
	v_mfma_f32_16x16x32_f16 v[114:117], v[130:133], v[150:153], v[114:117]
	ds_write_b128 v161, v[54:57] offset:16384
	global_load_dwordx4 v[54:57], v[168:169], off
	s_waitcnt lgkmcnt(5)
	v_mfma_f32_16x16x32_f16 v[110:113], v[244:247], v[192:195], v[110:113]
	v_mfma_f32_16x16x32_f16 v[106:109], v[248:251], v[192:195], v[106:109]
	v_mfma_f32_16x16x32_f16 v[102:105], v[252:255], v[192:195], v[102:105]
	v_mfma_f32_16x16x32_f16 v[98:101], v[130:133], v[192:195], v[98:101]
	s_waitcnt vmcnt(15)
	ds_write_b128 v161, v[70:73] offset:20480
	v_add_co_u32_e32 v70, vcc, s81, v168
	s_nop 1
	v_addc_co_u32_e32 v71, vcc, 0, v169, vcc
	global_load_dwordx4 v[70:73], v[70:71], off
	s_waitcnt lgkmcnt(4)
	v_mfma_f32_16x16x32_f16 v[94:97], v[244:247], v[196:199], v[94:97]
	v_mfma_f32_16x16x32_f16 v[90:93], v[248:251], v[196:199], v[90:93]
	v_mfma_f32_16x16x32_f16 v[86:89], v[252:255], v[196:199], v[86:89]
	v_mfma_f32_16x16x32_f16 v[82:85], v[130:133], v[196:199], v[82:85]
	s_waitcnt vmcnt(15)
	ds_write_b128 v161, v[74:77] offset:24576
	v_add_co_u32_e32 v74, vcc, s97, v168
	s_nop 1
	v_addc_co_u32_e32 v75, vcc, 0, v169, vcc
	global_load_dwordx4 v[74:77], v[74:75], off
	s_waitcnt lgkmcnt(4)
	v_mfma_f32_16x16x32_f16 v[14:17], v[244:247], v[200:203], v[14:17]
	v_mfma_f32_16x16x32_f16 v[10:13], v[248:251], v[200:203], v[10:13]
	v_mfma_f32_16x16x32_f16 v[6:9], v[252:255], v[200:203], v[6:9]
	v_mfma_f32_16x16x32_f16 v[2:5], v[130:133], v[200:203], v[2:5]
	s_waitcnt vmcnt(15)
	ds_write_b128 v161, v[78:81] offset:28672
	v_add_co_u32_e32 v78, vcc, s27, v168
	s_nop 1
	v_addc_co_u32_e32 v79, vcc, 0, v169, vcc
	global_load_dwordx4 v[78:81], v[78:79], off
	s_waitcnt lgkmcnt(0)
	s_barrier
	s_cbranch_scc1 .LBB0_1457
; template <int NJ>
; __device__ __forceinline__ void gres_tile(const Params& p, const f16* A, int lda, const f16* W, int K, const float* mod,
;                                           bool first_in, f16* sA, f16* sB, int m0, int n0) {
;     ...
;   for (int i = 0; i < 4; ++i) {
;     int m = m0 + wm * 64 + i * 16 + (lane & 15);
;     const float* xi = xrow_in(p, first_in ? 0 : 1, m);
;     float* xo = xrow_out(p, m);
;     const float* gt = mod + (size_t)modrow_of(m) * 6 * DM;
; #pragma unroll
;     for (int j = 0; j < NJ; ++j) {
;       int n = n0 + wn * (NJ * 16) + j * 16 + 4 * (lane >> 4);
;       float4 xv = *(const float4*)(xi + n);
;       float4 gv = *(const float4*)(gt + n);
;       float4 o;
;       o.x = xv.x + gv.x * acc[i][j][0];
;       o.y = xv.y + gv.y * acc[i][j][1];
;       o.z = xv.z + gv.z * acc[i][j][2];
;       o.w = xv.w + gv.w * acc[i][j][3];
;       *(float4*)(xo + n) = o;
;     }
;   }
	s_waitcnt vmcnt(15)
	v_or_b32_e32 v18, s6, v154
	v_add_u32_e32 v21, v18, v160
	v_cmp_gt_i32_e32 vcc, s80, v21
	v_ashrrev_i32_e32 v20, 31, v21
	s_waitcnt vmcnt(11)
	v_add_u32_e32 v22, 0xffff8000, v21
	v_cndmask_b32_e32 v23, 0, v20, vcc
	v_cndmask_b32_e32 v22, v22, v21, vcc
	v_cndmask_b32_e32 v25, v137, v1, vcc
	v_cndmask_b32_e32 v24, v136, v0, vcc
	v_lshlrev_b64 v[22:23], 12, v[22:23]
	v_lshrrev_b32_e32 v20, 18, v20
	v_lshl_add_u64 v[22:23], v[24:25], 0, v[22:23]
	v_add_u32_e32 v24, v21, v20
	v_lshl_or_b32 v18, s7, 7, v166
	v_ashrrev_i32_e32 v24, 14, v24
	v_ashrrev_i32_e32 v19, 31, v18
	v_cndmask_b32_e32 v24, 2, v24, vcc
	v_mul_hi_i32_i24_e32 v25, 0x6000, v24
	v_mul_i32_i24_e32 v24, 0x6000, v24
	v_lshlrev_b64 v[18:19], 2, v[18:19]
	v_lshl_add_u64 v[24:25], v[134:135], 0, v[24:25]
	v_lshl_add_u64 v[30:31], v[22:23], 0, v[18:19]
	v_lshl_add_u64 v[32:33], v[24:25], 0, v[18:19]
	global_load_dwordx4 v[22:25], v[30:31], off
	global_load_dwordx4 v[26:29], v[32:33], off
	s_add_i32 s5, s5, s26
	s_cmp_ge_i32 s5, s74
	s_waitcnt vmcnt(0)
	v_pk_fma_f32 v[22:23], v[126:127], v[26:27], v[22:23]
	v_pk_fma_f32 v[24:25], v[128:129], v[28:29], v[24:25]
	global_store_dwordx4 v[30:31], v[22:25], off
	global_load_dwordx4 v[22:25], v[30:31], off offset:64
	s_nop 0
	global_load_dwordx4 v[26:29], v[32:33], off offset:64
	s_waitcnt vmcnt(0)
	v_pk_fma_f32 v[22:23], v[122:123], v[26:27], v[22:23]
	v_pk_fma_f32 v[24:25], v[124:125], v[28:29], v[24:25]
	global_store_dwordx4 v[30:31], v[22:25], off offset:64
	global_load_dwordx4 v[22:25], v[30:31], off offset:128
	s_nop 0
	global_load_dwordx4 v[26:29], v[32:33], off offset:128
	s_waitcnt vmcnt(0)
	v_pk_fma_f32 v[22:23], v[118:119], v[26:27], v[22:23]
	v_pk_fma_f32 v[24:25], v[120:121], v[28:29], v[24:25]
	global_store_dwordx4 v[30:31], v[22:25], off offset:128
	global_load_dwordx4 v[22:25], v[30:31], off offset:192
	s_nop 0
	global_load_dwordx4 v[26:29], v[32:33], off offset:192
	s_waitcnt vmcnt(0)
	v_pk_fma_f32 v[22:23], v[114:115], v[26:27], v[22:23]
	v_pk_fma_f32 v[24:25], v[116:117], v[28:29], v[24:25]
	v_or_b32_e32 v26, 16, v21
	global_store_dwordx4 v[30:31], v[22:25], off offset:192
	v_cmp_gt_i32_e32 vcc, s80, v26
	s_nop 0
	v_ashrrev_i32_e32 v22, 31, v26
	v_add_u32_e32 v24, 0xffff8010, v21
	v_cndmask_b32_e32 v23, 0, v22, vcc
	v_cndmask_b32_e32 v22, v24, v26, vcc
	v_cndmask_b32_e32 v25, v137, v1, vcc
	v_cndmask_b32_e32 v24, v136, v0, vcc
	v_lshlrev_b64 v[22:23], 12, v[22:23]
	v_lshl_add_u64 v[22:23], v[24:25], 0, v[22:23]
	v_add_u32_e32 v24, v26, v20
	v_ashrrev_i32_e32 v24, 14, v24
	v_cndmask_b32_e32 v24, 2, v24, vcc
	v_mul_hi_i32_i24_e32 v25, 0x6000, v24
	v_mul_i32_i24_e32 v24, 0x6000, v24
	v_lshl_add_u64 v[24:25], v[134:135], 0, v[24:25]
	v_lshl_add_u64 v[30:31], v[22:23], 0, v[18:19]
	v_lshl_add_u64 v[32:33], v[24:25], 0, v[18:19]
	global_load_dwordx4 v[22:25], v[30:31], off
	global_load_dwordx4 v[26:29], v[32:33], off
	s_waitcnt vmcnt(0)
	v_pk_fma_f32 v[22:23], v[110:111], v[26:27], v[22:23]
	v_pk_fma_f32 v[24:25], v[112:113], v[28:29], v[24:25]
	global_store_dwordx4 v[30:31], v[22:25], off
	global_load_dwordx4 v[22:25], v[30:31], off offset:64
	s_nop 0
	global_load_dwordx4 v[26:29], v[32:33], off offset:64
	s_waitcnt vmcnt(0)
	v_pk_fma_f32 v[22:23], v[106:107], v[26:27], v[22:23]
	v_pk_fma_f32 v[24:25], v[108:109], v[28:29], v[24:25]
	global_store_dwordx4 v[30:31], v[22:25], off offset:64
	global_load_dwordx4 v[22:25], v[30:31], off offset:128
	s_nop 0
	global_load_dwordx4 v[26:29], v[32:33], off offset:128
	s_waitcnt vmcnt(0)
	v_pk_fma_f32 v[22:23], v[102:103], v[26:27], v[22:23]
	v_pk_fma_f32 v[24:25], v[104:105], v[28:29], v[24:25]
	global_store_dwordx4 v[30:31], v[22:25], off offset:128
	global_load_dwordx4 v[22:25], v[30:31], off offset:192
	s_nop 0
	global_load_dwordx4 v[26:29], v[32:33], off offset:192
	s_waitcnt vmcnt(0)
	v_pk_fma_f32 v[22:23], v[98:99], v[26:27], v[22:23]
	v_pk_fma_f32 v[24:25], v[100:101], v[28:29], v[24:25]
	v_or_b32_e32 v26, 32, v21
	global_store_dwordx4 v[30:31], v[22:25], off offset:192
	v_cmp_gt_i32_e32 vcc, s80, v26
	s_nop 0
	v_ashrrev_i32_e32 v22, 31, v26
	v_add_u32_e32 v24, 0xffff8020, v21
	v_cndmask_b32_e32 v23, 0, v22, vcc
	v_cndmask_b32_e32 v22, v24, v26, vcc
	v_cndmask_b32_e32 v25, v137, v1, vcc
	v_cndmask_b32_e32 v24, v136, v0, vcc
	v_lshlrev_b64 v[22:23], 12, v[22:23]
	v_lshl_add_u64 v[22:23], v[24:25], 0, v[22:23]
	v_add_u32_e32 v24, v26, v20
	v_ashrrev_i32_e32 v24, 14, v24
	v_cndmask_b32_e32 v24, 2, v24, vcc
	v_mul_hi_i32_i24_e32 v25, 0x6000, v24
	v_mul_i32_i24_e32 v24, 0x6000, v24
	v_lshl_add_u64 v[24:25], v[134:135], 0, v[24:25]
	v_lshl_add_u64 v[30:31], v[22:23], 0, v[18:19]
	v_lshl_add_u64 v[32:33], v[24:25], 0, v[18:19]
	global_load_dwordx4 v[22:25], v[30:31], off
	global_load_dwordx4 v[26:29], v[32:33], off
	s_waitcnt vmcnt(0)
; template <int NJ>
; __device__ __forceinline__ void gres_tile(const Params& p, const f16* A, int lda, const f16* W, int K, const float* mod,
;                                           bool first_in, f16* sA, f16* sB, int m0, int n0) {
;     ...
;       o.x = xv.x + gv.x * acc[i][j][0];
;       o.y = xv.y + gv.y * acc[i][j][1];
;       o.z = xv.z + gv.z * acc[i][j][2];
;       o.w = xv.w + gv.w * acc[i][j][3];
;       *(float4*)(xo + n) = o;
;     }
;   }
; __device__ __forceinline__ void phase_gres(const Params& p, int l, const f16* A, int lda, const f16* W, int K, int gate_idx,
;                            bool first_in, f16* smem) {
;     ...
;   for (int u = blockIdx.x; u < 2 * (MT * NT - full); u += gridDim.x) {
;     const int t = full + (u >> 1);
;     gres_tile<2>(p, A, lda, W, K, mod, first_in, sA, sB, (t / NT) * 128, (t % NT) * 128 + (u & 1) * 64);
	v_pk_fma_f32 v[22:23], v[94:95], v[26:27], v[22:23]
	v_pk_fma_f32 v[24:25], v[96:97], v[28:29], v[24:25]
	global_store_dwordx4 v[30:31], v[22:25], off
	global_load_dwordx4 v[22:25], v[30:31], off offset:64
	s_nop 0
	global_load_dwordx4 v[26:29], v[32:33], off offset:64
	s_waitcnt vmcnt(0)
	v_pk_fma_f32 v[22:23], v[90:91], v[26:27], v[22:23]
	v_pk_fma_f32 v[24:25], v[92:93], v[28:29], v[24:25]
	global_store_dwordx4 v[30:31], v[22:25], off offset:64
	global_load_dwordx4 v[22:25], v[30:31], off offset:128
	s_nop 0
	global_load_dwordx4 v[26:29], v[32:33], off offset:128
	s_waitcnt vmcnt(0)
	v_pk_fma_f32 v[22:23], v[86:87], v[26:27], v[22:23]
	v_pk_fma_f32 v[24:25], v[88:89], v[28:29], v[24:25]
	global_store_dwordx4 v[30:31], v[22:25], off offset:128
	global_load_dwordx4 v[22:25], v[30:31], off offset:192
	s_nop 0
	global_load_dwordx4 v[26:29], v[32:33], off offset:192
	s_waitcnt vmcnt(0)
	v_pk_fma_f32 v[22:23], v[82:83], v[26:27], v[22:23]
	v_pk_fma_f32 v[24:25], v[84:85], v[28:29], v[24:25]
	v_or_b32_e32 v26, 48, v21
	global_store_dwordx4 v[30:31], v[22:25], off offset:192
	v_cmp_gt_i32_e32 vcc, s80, v26
	v_add_u32_e32 v21, 0xffff8030, v21
	v_ashrrev_i32_e32 v22, 31, v26
	v_add_u32_e32 v20, v26, v20
	v_cndmask_b32_e32 v23, 0, v22, vcc
	v_cndmask_b32_e32 v22, v21, v26, vcc
	v_ashrrev_i32_e32 v20, 14, v20
	v_cndmask_b32_e32 v25, v137, v1, vcc
	v_cndmask_b32_e32 v24, v136, v0, vcc
	v_lshlrev_b64 v[22:23], 12, v[22:23]
	v_cndmask_b32_e32 v20, 2, v20, vcc
	v_lshl_add_u64 v[22:23], v[24:25], 0, v[22:23]
	v_mul_hi_i32_i24_e32 v21, 0x6000, v20
	v_mul_i32_i24_e32 v20, 0x6000, v20
	v_lshl_add_u64 v[20:21], v[134:135], 0, v[20:21]
	v_lshl_add_u64 v[26:27], v[22:23], 0, v[18:19]
	v_lshl_add_u64 v[28:29], v[20:21], 0, v[18:19]
	global_load_dwordx4 v[18:21], v[26:27], off
	global_load_dwordx4 v[22:25], v[28:29], off
	s_waitcnt vmcnt(0)
	v_pk_fma_f32 v[14:15], v[14:15], v[22:23], v[18:19]
	v_pk_fma_f32 v[16:17], v[16:17], v[24:25], v[20:21]
	global_store_dwordx4 v[26:27], v[14:17], off
	global_load_dwordx4 v[14:17], v[26:27], off offset:64
	s_nop 0
	global_load_dwordx4 v[18:21], v[28:29], off offset:64
	s_waitcnt vmcnt(0)
	v_pk_fma_f32 v[10:11], v[10:11], v[18:19], v[14:15]
	v_pk_fma_f32 v[12:13], v[12:13], v[20:21], v[16:17]
	global_store_dwordx4 v[26:27], v[10:13], off offset:64
	global_load_dwordx4 v[10:13], v[26:27], off offset:128
	s_nop 0
	global_load_dwordx4 v[14:17], v[28:29], off offset:128
	s_waitcnt vmcnt(0)
	v_pk_fma_f32 v[6:7], v[6:7], v[14:15], v[10:11]
	v_pk_fma_f32 v[8:9], v[8:9], v[16:17], v[12:13]
	global_store_dwordx4 v[26:27], v[6:9], off offset:128
	global_load_dwordx4 v[6:9], v[26:27], off offset:192
	s_nop 0
	global_load_dwordx4 v[10:13], v[28:29], off offset:192
	s_waitcnt vmcnt(0)
	v_pk_fma_f32 v[2:3], v[2:3], v[10:11], v[6:7]
	v_pk_fma_f32 v[4:5], v[4:5], v[12:13], v[8:9]
	global_store_dwordx4 v[26:27], v[2:5], off offset:192
	s_cbranch_scc0 .LBB0_1456
.LBB0_1459:
	s_and_b64 vcc, exec, s[8:9]
	s_cbranch_vccnz .LBB0_1464
	s_cmp_eq_u32 s4, 3
	s_cbranch_scc1 .LBB0_1464
	v_and_b32_e32 v4, 56, v159
	v_mad_i64_i32 v[2:3], s[6:7], v156, s96, v[140:141]
	v_lshlrev_b32_e32 v164, 1, v4
	v_and_b32_e32 v92, 0xffffffc0, v158
	v_and_b32_e32 v8, 32, v157
	v_lshl_add_u64 v[82:83], v[2:3], 0, v[164:165]
	v_mad_i64_i32 v[2:3], s[6:7], v156, s96, v[138:139]
	s_movk_i32 s5, 0x48
	v_or_b32_e32 v6, v92, v154
	v_or_b32_e32 v9, v8, v154
	v_mul_lo_u32 v5, v156, s5
	v_and_b32_e32 v7, 24, v157
	v_mul_u32_u24_e32 v9, 0x48, v9
	v_lshl_add_u64 v[84:85], v[2:3], 0, v[164:165]
	v_mul_lo_u32 v2, v6, s5
	v_add_lshl_u32 v93, v5, v4, 1
	v_add_lshl_u32 v94, v2, v7, 1
	v_add_lshl_u32 v95, v9, v7, 1
	v_and_or_b32 v96, v155, 12, v8
	v_lshrrev_b32_e32 v242, 3, v171
	v_xor_b32_e32 v243, v242, v171
	v_and_b32_e32 v243, 7, v243
	v_lshlrev_b32_e32 v243, 4, v243
	v_lshl_or_b32 v93, v242, 7, v243
	v_bfe_u32 v242, v171, 4, 2
	v_xor_b32_e32 v242, v242, v171
	v_and_b32_e32 v242, 7, v242
	v_lshlrev_b32_e32 v242, 4, v242
	v_lshrrev_b32_e32 v243, 1, v171
	v_and_b32_e32 v243, 64, v243
	v_and_or_b32 v243, v171, 15, v243
	v_lshl_or_b32 v94, v243, 7, v242
	v_lshrrev_b32_e32 v243, 1, v171
	v_and_b32_e32 v243, 32, v243
	v_and_or_b32 v243, v171, 15, v243
	v_lshl_or_b32 v95, v243, 7, v242
	v_xor_b32_e32 v242, 64, v94
	v_xor_b32_e32 v243, 64, v95
	s_mov_b32 s5, s95

; __global__ void __launch_bounds__(256, 2) mega(Params p_unused) {
;   cg::grid_group grid = cg::this_grid();
;   __shared__ __attribute__((aligned(16))) unsigned char smem_raw[SMEM_BYTES];
	.amdhsa_kernel _Z4mega6Params
		.amdhsa_group_segment_fixed_size 73744
		.amdhsa_private_segment_fixed_size 0
		.amdhsa_kernarg_size 536
		.amdhsa_user_sgpr_count 2
		.amdhsa_user_sgpr_dispatch_ptr 0
		.amdhsa_user_sgpr_queue_ptr 0
		.amdhsa_user_sgpr_kernarg_segment_ptr 1
		.amdhsa_user_sgpr_dispatch_id 0
		.amdhsa_user_sgpr_kernarg_preload_length 0
		.amdhsa_user_sgpr_kernarg_preload_offset 0
		.amdhsa_user_sgpr_private_segment_size 0
		.amdhsa_uses_dynamic_stack 0
		.amdhsa_enable_private_segment 0
		.amdhsa_system_sgpr_workgroup_id_x 1
		.amdhsa_system_sgpr_workgroup_id_y 0
		.amdhsa_system_sgpr_workgroup_id_z 0
		.amdhsa_system_sgpr_workgroup_info 0
		.amdhsa_system_vgpr_workitem_id 2
		.amdhsa_next_free_vgpr 256
		.amdhsa_next_free_sgpr 100
		.amdhsa_accum_offset 256
		.amdhsa_reserve_vcc 1
		.amdhsa_float_round_mode_32 0
		.amdhsa_float_round_mode_16_64 0
		.amdhsa_float_denorm_mode_32 3
		.amdhsa_float_denorm_mode_16_64 3
		.amdhsa_dx10_clamp 1
		.amdhsa_ieee_mode 1
		.amdhsa_fp16_overflow 0
		.amdhsa_tg_split 0
		.amdhsa_exception_fp_ieee_invalid_op 0
		.amdhsa_exception_fp_denorm_src 0
		.amdhsa_exception_fp_ieee_div_zero 0
		.amdhsa_exception_fp_ieee_overflow 0
		.amdhsa_exception_fp_ieee_underflow 0
		.amdhsa_exception_fp_ieee_inexact 0
		.amdhsa_exception_int_div_zero 0
	.end_amdhsa_kernel

; __global__ void __launch_bounds__(256, 2) mega(Params p_unused) {
;   cg::grid_group grid = cg::this_grid();
;   __shared__ __attribute__((aligned(16))) unsigned char smem_raw[SMEM_BYTES];
amdhsa.kernels:
  - .agpr_count:     0
    .args:
      - .offset:         0
        .size:           280
        .value_kind:     by_value
      - .offset:         280
        .size:           4
        .value_kind:     hidden_block_count_x
      - .offset:         284
        .size:           4
        .value_kind:     hidden_block_count_y
      - .offset:         288
        .size:           4
        .value_kind:     hidden_block_count_z
      - .offset:         292
        .size:           2
        .value_kind:     hidden_group_size_x
      - .offset:         294
        .size:           2
        .value_kind:     hidden_group_size_y
      - .offset:         296
        .size:           2
        .value_kind:     hidden_group_size_z
      - .offset:         298
        .size:           2
        .value_kind:     hidden_remainder_x
      - .offset:         300
        .size:           2
        .value_kind:     hidden_remainder_y
      - .offset:         302
        .size:           2
        .value_kind:     hidden_remainder_z
      - .offset:         320
        .size:           8
        .value_kind:     hidden_global_offset_x
      - .offset:         328
        .size:           8
        .value_kind:     hidden_global_offset_y
      - .offset:         336
        .size:           8
        .value_kind:     hidden_global_offset_z
      - .offset:         344
        .size:           2
        .value_kind:     hidden_grid_dims
      - .offset:         368
        .size:           8
        .value_kind:     hidden_multigrid_sync_arg
    .group_segment_fixed_size: 73744
    .kernarg_segment_align: 8
    .kernarg_segment_size: 536
    .language:       OpenCL C
    .language_version:
      - 2
      - 0
    .max_flat_workgroup_size: 256
    .name:           _Z4mega6Params
    .private_segment_fixed_size: 0
    .sgpr_count:     106
    .sgpr_spill_count: 56
    .symbol:         _Z4mega6Params.kd
    .uniform_work_group_size: 1
    .uses_dynamic_stack: false
    .vgpr_count:     256
    .vgpr_spill_count: 0
    .wavefront_size: 64
